# hyena long-conv lag loop software pipelined by hand: Toeplitz window via dword-granular LDS reads + alignbit (no cndmask network), window and all 8 z fragments of the next lag prefetched under the 8 M
# speedup vs baseline: 1.2849x; 1.0119x over previous
; DI void hyena_conv(const bf16_t* sK, const bf16_t* sZ, f32x16 (&acc)[4], int q, int lane) {
;   const int r = lane & 31, h = lane >> 5;
;   const int phi = (7 - r) & 7;
;   const bool pb0 = (phi >> 1) & 1, pb1 = (phi >> 2) & 1;
;   const unsigned psh = (phi & 1) * 16;
; #pragma unroll
;   for (int bb = 0; bb < 4; ++bb)
; #pragma unroll
;     for (int i = 0; i < 16; ++i) acc[bb][i] = 0.f;
;   int dlo = 32 * q - 127, dhi = 32 * q + 31;
;   asm volatile("" : "+s"(dlo), "+s"(dhi));
;   for (int d = dlo; d < dhi; d += 2) {
;     HY_BODY(d)
;     HY_BODY(d + 1)
;   }
;   HY_BODY(dhi)
; DI void hyena_item(const Params& p, int layer, int c, int bh, char* smem) {
;     ...
;   const float inv0 = 1.0f / (red[0] + red[1] + red[2] + red[3]);
;   const float inv1 = 1.0f / (red[4] + red[5] + red[6] + red[7]);
;   const float bias0 = p.hy_bias[(layer * 2 + 0) * 256 + c], bias1 = p.hy_bias[(layer * 2 + 1) * 256 + c];
;   f32x16 acc[4];
;   const int q = __builtin_amdgcn_readfirstlane(wave), n = lane & 31, h = lane >> 5;
;   const int i = 32 * q + n;
;   hyena_conv(sK, sZ, acc, q, lane);
.LBB0_577:
	s_or_b64 exec, exec, s[36:37]
	s_add_i32 s0, s12, s74
	s_ashr_i32 s1, s0, 31
	v_readlane_b32 s36, v236, 5
	s_lshl_b64 s[0:1], s[0:1], 2
	v_readlane_b32 s38, v236, 7
	v_readlane_b32 s39, v236, 8
	s_add_u32 s0, s38, s0
	s_addc_u32 s1, s39, s1
	s_waitcnt lgkmcnt(0)
	s_barrier
	ds_read_b128 v[68:71], v193
	ds_read_b128 v[64:67], v194
	global_load_dword v102, v141, s[0:1]
	global_load_dword v88, v141, s[0:1] offset:1024
	v_readfirstlane_b32 s29, v32
	s_lshl_b32 s1, s29, 5
	v_bitop3_b32 v0, v98, 2, v98 bitop3:0xc
	s_add_i32 s28, s1, 0xffffff81
	s_or_b32 s11, s1, 31
	s_mov_b32 s80, s55
	v_and_b32_e32 v97, 31, v98
	v_bitop3_b32 v85, v98, 7, v98 bitop3:0xc
	v_cmp_eq_u32_e64 s[54:55], 0, v0
	s_mov_b32 s36, s28
	s_mov_b32 s0, s11
	v_mov_b32_e32 v63, 0
	v_lshrrev_b32_e32 v0, 1, v98
	v_cmp_lt_u32_e64 s[52:53], 3, v85
	v_lshlrev_b32_e32 v83, 4, v85
	s_cmp_ge_i32 s36, s0
	v_add_u32_e32 v103, v85, v97
	v_add_u32_e32 v105, s1, v97
	s_mulk_i32 s29, 0xa00
	v_and_b32_e32 v87, 16, v0
	v_mov_b32_e32 v62, v63
	v_mov_b32_e32 v61, v63
	v_mov_b32_e32 v60, v63
	v_mov_b32_e32 v59, v63
	v_mov_b32_e32 v58, v63
	v_mov_b32_e32 v57, v63
	v_mov_b32_e32 v56, v63
	v_mov_b32_e32 v55, v63
	v_mov_b32_e32 v54, v63
	v_mov_b32_e32 v53, v63
	v_mov_b32_e32 v52, v63
	v_mov_b32_e32 v51, v63
	v_mov_b32_e32 v50, v63
	v_mov_b32_e32 v49, v63
	v_mov_b32_e32 v48, v63
	v_mov_b32_e32 v47, v63
	v_mov_b32_e32 v46, v63
	v_mov_b32_e32 v45, v63
	v_mov_b32_e32 v44, v63
	v_mov_b32_e32 v43, v63
	v_mov_b32_e32 v42, v63
	v_mov_b32_e32 v41, v63
	v_mov_b32_e32 v40, v63
	v_mov_b32_e32 v39, v63
	v_mov_b32_e32 v38, v63
	v_mov_b32_e32 v37, v63
	v_mov_b32_e32 v36, v63
	v_mov_b32_e32 v35, v63
	v_mov_b32_e32 v34, v63
	v_mov_b32_e32 v33, v63
	v_mov_b32_e32 v32, v63
	v_mov_b32_e32 v31, v63
	v_mov_b32_e32 v30, v63
	v_mov_b32_e32 v29, v63
	v_mov_b32_e32 v28, v63
	v_mov_b32_e32 v27, v63
	v_mov_b32_e32 v26, v63
	v_mov_b32_e32 v25, v63
	v_mov_b32_e32 v24, v63
	v_mov_b32_e32 v23, v63
	v_mov_b32_e32 v22, v63
	v_mov_b32_e32 v21, v63
	v_mov_b32_e32 v20, v63
	v_mov_b32_e32 v19, v63
	v_mov_b32_e32 v18, v63
	v_mov_b32_e32 v17, v63
	v_mov_b32_e32 v16, v63
	v_mov_b32_e32 v15, v63
	v_mov_b32_e32 v14, v63
	v_mov_b32_e32 v13, v63
	v_mov_b32_e32 v12, v63
	v_mov_b32_e32 v11, v63
	v_mov_b32_e32 v10, v63
	v_mov_b32_e32 v9, v63
	v_mov_b32_e32 v8, v63
	v_mov_b32_e32 v7, v63
	v_mov_b32_e32 v6, v63
	v_mov_b32_e32 v5, v63
	v_mov_b32_e32 v4, v63
	v_mov_b32_e32 v3, v63
	v_mov_b32_e32 v2, v63
	v_mov_b32_e32 v1, v63
	v_mov_b32_e32 v0, v63
	v_readlane_b32 s37, v236, 6
	v_readlane_b32 s40, v236, 9
	v_readlane_b32 s41, v236, 10
	v_readlane_b32 s42, v236, 11
	v_readlane_b32 s43, v236, 12
	v_readlane_b32 s44, v236, 13
	v_readlane_b32 s45, v236, 14
	v_readlane_b32 s46, v236, 15
	v_readlane_b32 s47, v236, 16
	v_readlane_b32 s48, v236, 17
	v_readlane_b32 s49, v236, 18
	v_readlane_b32 s50, v236, 19
	v_readlane_b32 s51, v236, 20
	s_cbranch_scc1 .LBB0_580
	v_subrev_u32_e32 v0, s36, v105
	s_movk_i32 s38, 0x50
	v_mul_lo_u32 v0, v0, s38
	s_lshl_b32 s37, s36, 6
	v_add_u32_e32 v91, 0xa00, v0
	v_lshl_add_u32 v0, v103, 1, s37
	v_sub_u32_e32 v93, 0, v0
	v_mov_b32_e32 v0, s29
	v_mad_u32_u24 v0, v97, s38, v0
	s_mul_i32 s37, s36, 0x50
	v_subrev_u32_e32 v0, s37, v0
	v_add_u32_e32 v95, 0x9b0, v0
	v_mov_b32_e32 v0, 0
	s_movk_i32 s27, 0x50
	v_mov_b32_e32 v1, v0
	v_mov_b32_e32 v2, v0
	v_mov_b32_e32 v3, v0
	v_mov_b32_e32 v4, v0
	v_mov_b32_e32 v5, v0
	v_mov_b32_e32 v6, v0
	v_mov_b32_e32 v7, v0
	v_mov_b32_e32 v8, v0
	v_mov_b32_e32 v9, v0
	v_mov_b32_e32 v10, v0
	v_mov_b32_e32 v11, v0
	v_mov_b32_e32 v12, v0
	v_mov_b32_e32 v13, v0
	v_mov_b32_e32 v14, v0
	v_mov_b32_e32 v15, v0
	v_mov_b32_e32 v16, v0
	v_mov_b32_e32 v17, v0
	v_mov_b32_e32 v18, v0
	v_mov_b32_e32 v19, v0
	v_mov_b32_e32 v20, v0
	v_mov_b32_e32 v21, v0
	v_mov_b32_e32 v22, v0
	v_mov_b32_e32 v23, v0
	v_mov_b32_e32 v24, v0
	v_mov_b32_e32 v25, v0
	v_mov_b32_e32 v26, v0
	v_mov_b32_e32 v27, v0
	v_mov_b32_e32 v28, v0
	v_mov_b32_e32 v29, v0
	v_mov_b32_e32 v30, v0
	v_mov_b32_e32 v31, v0
	v_mov_b32_e32 v32, v0
	v_mov_b32_e32 v33, v0
	v_mov_b32_e32 v34, v0
	v_mov_b32_e32 v35, v0
	v_mov_b32_e32 v36, v0
	v_mov_b32_e32 v37, v0
	v_mov_b32_e32 v38, v0
	v_mov_b32_e32 v39, v0
	v_mov_b32_e32 v40, v0
	v_mov_b32_e32 v41, v0
	v_mov_b32_e32 v42, v0
	v_mov_b32_e32 v43, v0
	v_mov_b32_e32 v44, v0
	v_mov_b32_e32 v45, v0
	v_mov_b32_e32 v46, v0
	v_mov_b32_e32 v47, v0
	v_mov_b32_e32 v48, v0
	v_mov_b32_e32 v49, v0
	v_mov_b32_e32 v50, v0
	v_mov_b32_e32 v51, v0
	v_mov_b32_e32 v52, v0
	v_mov_b32_e32 v53, v0
	v_mov_b32_e32 v54, v0
	v_mov_b32_e32 v55, v0
	v_mov_b32_e32 v56, v0
	v_mov_b32_e32 v57, v0
	v_mov_b32_e32 v58, v0
	v_mov_b32_e32 v59, v0
	v_mov_b32_e32 v60, v0
	v_mov_b32_e32 v61, v0
	v_mov_b32_e32 v62, v0
	v_mov_b32_e32 v63, v0
	v_and_b32_e32 v241, 6, v85
	v_lshl_add_u32 v241, v241, 1, v87
	v_add_u32_e32 v241, 0x10fbe, v241
	v_add_u32_e32 v240, v93, v241
	ds_read2_b32 v[242:243], v240 offset0:16 offset1:17
	ds_read2_b32 v[244:245], v240 offset0:18 offset1:19
	ds_read2_b32 v[246:247], v240 offset0:20 offset1:24
	ds_read2_b32 v[248:249], v240 offset0:25 offset1:26
	ds_read2_b32 v[250:251], v240 offset0:27 offset1:28
	v_add_u32_e32 v101, v91, v87
	ds_read_b128 v[144:147], v101
	ds_read_b128 v[148:151], v101 offset:32
	ds_read_b128 v[152:155], v101 offset:15360
	ds_read_b128 v[156:159], v101 offset:15392
	ds_read_b128 v[160:163], v101 offset:30720
	ds_read_b128 v[164:167], v101 offset:30752
	ds_read_b128 v[168:171], v101 offset:46080
	ds_read_b128 v[172:175], v101 offset:46112
; DI void hyena_conv(const bf16_t* sK, const bf16_t* sZ, f32x16 (&acc)[4], int q, int lane) {
;   const int r = lane & 31, h = lane >> 5;
;   const int phi = (7 - r) & 7;
;   const bool pb0 = (phi >> 1) & 1, pb1 = (phi >> 2) & 1;
;   const unsigned psh = (phi & 1) * 16;
; #pragma unroll
;   for (int bb = 0; bb < 4; ++bb)
; #pragma unroll
;     for (int i = 0; i < 16; ++i) acc[bb][i] = 0.f;
;   int dlo = 32 * q - 127, dhi = 32 * q + 31;
;   asm volatile("" : "+s"(dlo), "+s"(dhi));
;   for (int d = dlo; d < dhi; d += 2) {
;     HY_BODY(d)
;     HY_BODY(d + 1)
;   }
;   HY_BODY(dhi)
; }
.LBB0_579:
	s_waitcnt lgkmcnt(0)
	v_alignbit_b32 v72, v243, v242, v83
	v_alignbit_b32 v73, v244, v243, v83
	v_alignbit_b32 v74, v245, v244, v83
	v_alignbit_b32 v75, v246, v245, v83
	v_alignbit_b32 v76, v248, v247, v83
	v_alignbit_b32 v77, v249, v248, v83
	v_alignbit_b32 v78, v250, v249, v83
	v_alignbit_b32 v79, v251, v250, v83
	ds_read2_b32 v[242:243], v240 offset0:0 offset1:1
	ds_read2_b32 v[244:245], v240 offset0:2 offset1:3
	ds_read2_b32 v[246:247], v240 offset0:4 offset1:8
	ds_read2_b32 v[248:249], v240 offset0:9 offset1:10
	ds_read2_b32 v[250:251], v240 offset0:11 offset1:12
	v_add_u32_e32 v99, v95, v87
	v_mfma_f32_32x32x16_bf16 v[48:63], v[72:75], v[144:147], v[48:63]
	ds_read_b128 v[176:179], v99
	v_mfma_f32_32x32x16_bf16 v[48:63], v[76:79], v[148:151], v[48:63]
	ds_read_b128 v[180:183], v99 offset:32
	s_add_i32 s36, s36, 2
	v_add_u32_e32 v91, 0xffffff60, v91
	v_add_u32_e32 v93, 0xffffff80, v93
	s_cmp_lt_i32 s36, s0
	v_mfma_f32_32x32x16_bf16 v[32:47], v[72:75], v[152:155], v[32:47]
	ds_read_b128 v[184:187], v99 offset:15360
	v_mfma_f32_32x32x16_bf16 v[32:47], v[76:79], v[156:159], v[32:47]
	ds_read_b128 v[212:215], v99 offset:15392
	v_mfma_f32_32x32x16_bf16 v[16:31], v[72:75], v[160:163], v[16:31]
	ds_read_b128 v[216:219], v99 offset:30720
	v_mfma_f32_32x32x16_bf16 v[16:31], v[76:79], v[164:167], v[16:31]
	ds_read_b128 v[220:223], v99 offset:30752
	v_mfma_f32_32x32x16_bf16 v[0:15], v[72:75], v[168:171], v[0:15]
	ds_read_b128 v[224:227], v99 offset:46080
	v_mfma_f32_32x32x16_bf16 v[0:15], v[76:79], v[172:175], v[0:15]
	ds_read_b128 v[228:231], v99 offset:46112
	s_waitcnt lgkmcnt(0)
	v_alignbit_b32 v72, v243, v242, v83
	v_alignbit_b32 v73, v244, v243, v83
	v_alignbit_b32 v74, v245, v244, v83
	v_alignbit_b32 v75, v246, v245, v83
	v_alignbit_b32 v76, v248, v247, v83
	v_alignbit_b32 v77, v249, v248, v83
	v_alignbit_b32 v78, v250, v249, v83
	v_alignbit_b32 v79, v251, v250, v83
	v_add_u32_e32 v240, v93, v241
	ds_read2_b32 v[242:243], v240 offset0:16 offset1:17
	ds_read2_b32 v[244:245], v240 offset0:18 offset1:19
	ds_read2_b32 v[246:247], v240 offset0:20 offset1:24
	ds_read2_b32 v[248:249], v240 offset0:25 offset1:26
	ds_read2_b32 v[250:251], v240 offset0:27 offset1:28
	v_add_u32_e32 v101, v91, v87
	v_mfma_f32_32x32x16_bf16 v[48:63], v[72:75], v[176:179], v[48:63]
	ds_read_b128 v[144:147], v101
	v_mfma_f32_32x32x16_bf16 v[48:63], v[76:79], v[180:183], v[48:63]
	ds_read_b128 v[148:151], v101 offset:32
	v_add_u32_e32 v95, 0xffffff60, v95
	v_mfma_f32_32x32x16_bf16 v[32:47], v[72:75], v[184:187], v[32:47]
	ds_read_b128 v[152:155], v101 offset:15360
	v_mfma_f32_32x32x16_bf16 v[32:47], v[76:79], v[212:215], v[32:47]
	ds_read_b128 v[156:159], v101 offset:15392
	v_mfma_f32_32x32x16_bf16 v[16:31], v[72:75], v[216:219], v[16:31]
	ds_read_b128 v[160:163], v101 offset:30720
	v_mfma_f32_32x32x16_bf16 v[16:31], v[76:79], v[220:223], v[16:31]
	ds_read_b128 v[164:167], v101 offset:30752
	v_mfma_f32_32x32x16_bf16 v[0:15], v[72:75], v[224:227], v[0:15]
	ds_read_b128 v[168:171], v101 offset:46080
	v_mfma_f32_32x32x16_bf16 v[0:15], v[76:79], v[228:231], v[0:15]
	ds_read_b128 v[172:175], v101 offset:46112
	s_cbranch_scc1 .LBB0_579

; DI unsigned pack2(float lo, float hi) { f32x2_t v = {lo, hi}; bf16x2_t r = __builtin_convertvector(v, bf16x2_t); return __builtin_bit_cast(unsigned, r); }
; DI float rbf(float x) { return bf2f(f2bf(x)); }
; DI void hy_conv4(const HyRaw4& r, int t0, float w0, float w1, float w2, float wb, float (&o)[4]) {
;   const float xm = t0 > 0 ? bf2f(r.m) : 0.f, xp = t0 + 4 < SEQ ? bf2f(r.pz) : 0.f;
;   const float e0 = bf2f((bf16_t)(r.v.x & 0xffff)), e1 = bf2f((bf16_t)(r.v.x >> 16)), e2 = bf2f((bf16_t)(r.v.y & 0xffff)), e3 = bf2f((bf16_t)(r.v.y >> 16));
;   o[0] = rbf(xm * w0 + e0 * w1 + e1 * w2 + wb);
;   o[1] = rbf(e0 * w0 + e1 * w1 + e2 * w2 + wb);
;   o[2] = rbf(e1 * w0 + e2 * w1 + e3 * w2 + wb);
;   o[3] = rbf(e2 * w0 + e3 * w1 + xp * w2 + wb);
; }
; DI void hyena_item(const Params& p, int layer, int c, int bh, char* smem) {
;     ...
;   const float inv0 = 1.0f / (red[0] + red[1] + red[2] + red[3]);
;   const float inv1 = 1.0f / (red[4] + red[5] + red[6] + red[7]);
;   const float bias0 = p.hy_bias[(layer * 2 + 0) * 256 + c], bias1 = p.hy_bias[(layer * 2 + 1) * 256 + c];
;   f32x16 acc[4];
;   const int q = __builtin_amdgcn_readfirstlane(wave), n = lane & 31, h = lane >> 5;
;   const int i = 32 * q + n;
;   hyena_conv(sK, sZ, acc, q, lane);
;   __syncthreads();
;   kr = (const bf16_t*)(p.ws + OFF_KREV) + ((size_t)(layer * 2 + 1) * 256 + c) * 8192;
;   for (int ii = tid; ii < 1024; ii += 256) *(uint4*)(sK + ii * 8) = *(const uint4*)(kr + ii * 8);
; #pragma unroll
;   for (int bb = 0; bb < 4; ++bb) {
;     const bf16_t* x1 = HT + (((size_t)1 * NB + bh * 4 + bb) * 256 + c) * SEQ;
;     bf16_t* zw = sZ + bb * ZROW;
; #pragma unroll
;     for (int g = 0; g < 4; ++g) {
;       const int off = 8 * g + 4 * h;
;       float xa[4];
;       hy_conv4(hy_raw4(x1, i * 32 + off), i * 32 + off, aw0, aw1, aw2, awb, xa);
;       uint2* zp = (uint2*)(zw + (i + 32) * ZB + off);
;       uint2 vv = *zp;
;       float z0 = xa[0] * (acc[bb][4 * g + 0] * inv0 + bf2f((bf16_t)(vv.x & 0xffff)) * bias0);
;       float z1 = xa[1] * (acc[bb][4 * g + 1] * inv0 + bf2f((bf16_t)(vv.x >> 16)) * bias0);
;       float z2 = xa[2] * (acc[bb][4 * g + 2] * inv0 + bf2f((bf16_t)(vv.y & 0xffff)) * bias0);
;       float z3 = xa[3] * (acc[bb][4 * g + 3] * inv0 + bf2f((bf16_t)(vv.y >> 16)) * bias0);
;       uint2 o; o.x = pack2(z0, z1); o.y = pack2(z2, z3);
;       *zp = o;
;     }
.LBB0_583:
	s_or_b64 exec, exec, s[0:1]
	v_add_f32_e32 v68, v68, v69
	v_add_f32_e32 v68, v68, v70
	v_add_f32_e32 v68, v68, v71
	v_div_scale_f32 v69, s[0:1], v68, v68, 1.0
	v_rcp_f32_e32 v70, v69
	s_movk_i32 s38, 0xffc
	v_fma_f32 v71, -v69, v70, 1.0
	v_fmac_f32_e32 v70, v71, v70
	v_div_scale_f32 v71, vcc, 1.0, v68, 1.0
	v_mul_f32_e32 v72, v71, v70
	v_fma_f32 v73, -v69, v72, v71
	v_fmac_f32_e32 v72, v73, v70
	v_fma_f32 v69, -v69, v72, v71
	v_div_fmas_f32 v69, v69, v70, v72
	s_lshl_b32 vcc_lo, s93, 10
	s_or_b32 s0, vcc_lo, 0x800
	v_div_fixup_f32 v104, v69, v68, 1.0
	v_lshrrev_b32_e32 v68, 3, v98
	s_add_u32 s0, s0, s12
	v_and_b32_e32 v113, 4, v68
	v_lshlrev_b32_e32 v98, 5, v91
	s_addc_u32 s1, 0, s13
	v_or_b32_e32 v100, v98, v113
	s_lshl_b64 s[0:1], s[0:1], 13
	v_ashrrev_i32_e32 v101, 31, v100
	s_add_u32 s0, s8, s0
	v_max_i32_e32 v70, 1, v100
	s_addc_u32 s1, s9, s1
	v_lshlrev_b64 v[76:77], 1, v[100:101]
	v_lshlrev_b32_e32 v81, 1, v70
	v_min_i32_e32 v70, 0xffb, v100
	v_lshl_add_u64 v[68:69], s[0:1], 0, v[76:77]
	v_ashrrev_i32_e32 v71, 31, v70
	global_load_dwordx2 v[68:69], v[68:69], off
	v_lshlrev_b64 v[78:79], 1, v[70:71]
	v_lshl_add_u64 v[70:71], s[0:1], 0, v[78:79]
	global_load_ushort v70, v[70:71], off offset:8
	v_cmp_gt_i32_e64 s[48:49], s38, v100
	global_load_ushort v73, v81, s[0:1] offset:-2
	v_mul_lo_u32 v72, v91, s27
	v_lshl_or_b32 v107, v113, 1, v72
	v_cmp_lt_i32_e64 s[50:51], 0, v100
	v_add_u32_e32 v89, 0x800, v107
	s_waitcnt vmcnt(2)
	v_lshlrev_b32_e32 v115, 16, v69
	v_and_b32_e32 v117, 0xffff0000, v69
	v_mov_b32_e32 v116, v115
	s_waitcnt vmcnt(1)
	v_lshlrev_b32_e32 v70, 16, v70
	v_and_b32_e32 v114, 0xffff0000, v68
	v_pk_mul_f32 v[120:121], v[92:93], v[116:117] op_sel_hi:[0,1]
	v_cndmask_b32_e64 v111, 0, v70, s[48:49]
	v_pk_fma_f32 v[120:121], v[96:97], v[114:115], v[120:121] op_sel_hi:[0,1,1]
	v_mov_b32_e32 v110, v117
	v_pk_fma_f32 v[110:111], v[90:91], v[110:111], v[120:121] op_sel_hi:[0,1,1]
	v_pk_add_f32 v[110:111], v[94:95], v[110:111] op_sel_hi:[0,1]
	s_waitcnt vmcnt(0)
	v_lshlrev_b32_e32 v73, 16, v73
	v_cvt_pk_bf16_f32 v93, v110, v111
	v_cndmask_b32_e64 v109, 0, v73, s[50:51]
	v_lshlrev_b32_e32 v112, 16, v68
	ds_read2_b64 v[72:75], v89 offset0:64 offset1:66
	ds_read2_b64 v[68:71], v89 offset0:68 offset1:70
	v_and_b32_e32 v111, 0xffff0000, v93
	v_lshlrev_b32_e32 v110, 16, v93
	v_mov_b32_e32 v93, v96
	v_mov_b32_e32 v108, v114
	v_pk_mul_f32 v[108:109], v[92:93], v[108:109]
	s_waitcnt lgkmcnt(1)
	v_lshlrev_b32_e32 v118, 16, v72
	v_pk_fma_f32 v[108:109], v[92:93], v[112:113], v[108:109] op_sel:[0,0,1] op_sel_hi:[1,0,0]
	v_and_b32_e32 v119, 0xffff0000, v72
	v_pk_fma_f32 v[108:109], v[90:91], v[114:115], v[108:109] op_sel_hi:[0,1,1]
	v_lshlrev_b32_e32 v72, 16, v73
	v_and_b32_e32 v73, 0xffff0000, v73
	v_pk_add_f32 v[108:109], v[94:95], v[108:109] op_sel_hi:[0,1]
	v_pk_mul_f32 v[116:117], v[102:103], v[118:119] op_sel_hi:[0,1]
	v_cvt_pk_bf16_f32 v99, v108, v109
	v_pk_mul_f32 v[72:73], v[102:103], v[72:73] op_sel_hi:[0,1]
	v_pk_fma_f32 v[48:49], v[104:105], v[48:49], v[116:117] op_sel_hi:[0,1,1]
	v_and_b32_e32 v109, 0xffff0000, v99
	v_lshlrev_b32_e32 v108, 16, v99
	v_pk_fma_f32 v[50:51], v[104:105], v[50:51], v[72:73] op_sel_hi:[0,1,1]
	v_or_b32_e32 v112, 8, v100
	v_ashrrev_i32_e32 v99, 31, v98
	v_pk_mul_f32 v[48:49], v[48:49], v[108:109]
	v_pk_mul_f32 v[50:51], v[50:51], v[110:111]
	v_mov_b32_e32 v101, v99
	v_max_i32_e32 v72, 1, v112
	v_cvt_pk_bf16_f32 v48, v48, v49
	v_cvt_pk_bf16_f32 v49, v50, v51
	v_lshlrev_b64 v[50:51], 1, v[100:101]
	v_lshlrev_b32_e32 v101, 1, v72
	v_min_i32_e32 v72, 0xffb, v112
	v_ashrrev_i32_e32 v73, 31, v72
	v_lshlrev_b64 v[72:73], 1, v[72:73]
	v_lshl_add_u64 v[108:109], s[0:1], 0, v[50:51]
	v_lshl_add_u64 v[114:115], s[0:1], 0, v[72:73]
	global_load_dwordx2 v[110:111], v[108:109], off offset:16
	v_cmp_lt_i32_e64 s[44:45], 0, v112
	v_cmp_gt_i32_e64 s[46:47], s38, v112
	global_load_ushort v112, v[114:115], off offset:8
	global_load_ushort v116, v101, s[0:1] offset:-2
	v_lshlrev_b32_e32 v120, 16, v74
	v_and_b32_e32 v121, 0xffff0000, v74
	v_lshlrev_b32_e32 v74, 16, v75
	v_and_b32_e32 v75, 0xffff0000, v75
	v_pk_mul_f32 v[74:75], v[102:103], v[74:75] op_sel_hi:[0,1]
	v_pk_fma_f32 v[54:55], v[104:105], v[54:55], v[74:75] op_sel_hi:[0,1,1]
	s_waitcnt vmcnt(2)
	v_lshlrev_b32_e32 v119, 16, v111
	v_and_b32_e32 v118, 0xffff0000, v110
	v_and_b32_e32 v111, 0xffff0000, v111
	s_waitcnt vmcnt(1)
	v_lshlrev_b32_e32 v112, 16, v112
	v_cndmask_b32_e64 v115, 0, v112, s[46:47]
	v_lshlrev_b32_e32 v112, 16, v110
	v_mov_b32_e32 v110, v119
	v_pk_mul_f32 v[122:123], v[92:93], v[110:111] op_sel_hi:[0,1]
	s_waitcnt vmcnt(0)
	v_lshlrev_b32_e32 v116, 16, v116
	v_pk_fma_f32 v[122:123], v[96:97], v[118:119], v[122:123] op_sel_hi:[0,1,1]
	v_mov_b32_e32 v114, v111
	v_cndmask_b32_e64 v117, 0, v116, s[44:45]
	v_pk_fma_f32 v[110:111], v[90:91], v[114:115], v[122:123] op_sel_hi:[0,1,1]
	v_pk_mul_f32 v[114:115], v[102:103], v[120:121] op_sel_hi:[0,1]
	v_mov_b32_e32 v116, v118
	v_pk_fma_f32 v[52:53], v[104:105], v[52:53], v[114:115] op_sel_hi:[0,1,1]
	v_pk_mul_f32 v[114:115], v[92:93], v[116:117]
	v_pk_add_f32 v[110:111], v[94:95], v[110:111] op_sel_hi:[0,1]
	v_pk_fma_f32 v[114:115], v[92:93], v[112:113], v[114:115] op_sel:[0,0,1] op_sel_hi:[1,0,0]
	v_cvt_pk_bf16_f32 v110, v110, v111
	v_pk_fma_f32 v[114:115], v[90:91], v[118:119], v[114:115] op_sel_hi:[0,1,1]
	v_pk_add_f32 v[114:115], v[94:95], v[114:115] op_sel_hi:[0,1]
	v_cvt_pk_bf16_f32 v112, v114, v115
	v_and_b32_e32 v111, 0xffff0000, v110
	v_lshlrev_b32_e32 v110, 16, v110
	v_and_b32_e32 v115, 0xffff0000, v112
	v_lshlrev_b32_e32 v114, 16, v112
	v_pk_mul_f32 v[52:53], v[52:53], v[114:115]
	v_pk_mul_f32 v[54:55], v[54:55], v[110:111]
	v_cvt_pk_bf16_f32 v52, v52, v53
	v_cvt_pk_bf16_f32 v53, v54, v55
	v_or_b32_e32 v54, 16, v100
	ds_write2_b64 v89, v[48:49], v[52:53] offset0:64 offset1:66
	v_max_i32_e32 v52, 1, v54
	v_lshlrev_b32_e32 v55, 1, v52
	v_min_i32_e32 v52, 0xffb, v54
	v_ashrrev_i32_e32 v53, 31, v52
	v_lshlrev_b64 v[52:53], 1, v[52:53]
	v_lshl_add_u64 v[74:75], s[0:1], 0, v[52:53]
	global_load_dwordx2 v[48:49], v[108:109], off offset:32
	global_load_ushort v110, v55, s[0:1] offset:-2
	v_cmp_lt_i32_e64 s[40:41], 0, v54
	v_cmp_gt_i32_e64 s[42:43], s38, v54
	global_load_ushort v54, v[74:75], off offset:8
	s_waitcnt lgkmcnt(1)
; DI unsigned pack2(float lo, float hi) { f32x2_t v = {lo, hi}; bf16x2_t r = __builtin_convertvector(v, bf16x2_t); return __builtin_bit_cast(unsigned, r); }
; DI bf16_t f2bf(float x) { return (bf16_t)(pack2(x, x) & 0xffffu); }
; DI float bf2f(bf16_t v) { return __uint_as_float(((unsigned)v) << 16); }
; DI float rbf(float x) { return bf2f(f2bf(x)); }
; DI void hy_conv4(const HyRaw4& r, int t0, float w0, float w1, float w2, float wb, float (&o)[4]) {
;   const float xm = t0 > 0 ? bf2f(r.m) : 0.f, xp = t0 + 4 < SEQ ? bf2f(r.pz) : 0.f;
;   const float e0 = bf2f((bf16_t)(r.v.x & 0xffff)), e1 = bf2f((bf16_t)(r.v.x >> 16)), e2 = bf2f((bf16_t)(r.v.y & 0xffff)), e3 = bf2f((bf16_t)(r.v.y >> 16));
;   o[0] = rbf(xm * w0 + e0 * w1 + e1 * w2 + wb);
;   o[1] = rbf(e0 * w0 + e1 * w1 + e2 * w2 + wb);
;   o[2] = rbf(e1 * w0 + e2 * w1 + e3 * w2 + wb);
;   o[3] = rbf(e2 * w0 + e3 * w1 + xp * w2 + wb);
; }
; DI void hyena_item(const Params& p, int layer, int c, int bh, char* smem) {
;     ...
;   for (int bb = 0; bb < 4; ++bb) {
;     const bf16_t* x1 = HT + (((size_t)1 * NB + bh * 4 + bb) * 256 + c) * SEQ;
;     bf16_t* zw = sZ + bb * ZROW;
; #pragma unroll
;     for (int g = 0; g < 4; ++g) {
;       const int off = 8 * g + 4 * h;
;       float xa[4];
;       hy_conv4(hy_raw4(x1, i * 32 + off), i * 32 + off, aw0, aw1, aw2, awb, xa);
;       uint2* zp = (uint2*)(zw + (i + 32) * ZB + off);
;       uint2 vv = *zp;
;       float z0 = xa[0] * (acc[bb][4 * g + 0] * inv0 + bf2f((bf16_t)(vv.x & 0xffff)) * bias0);
;       float z1 = xa[1] * (acc[bb][4 * g + 1] * inv0 + bf2f((bf16_t)(vv.x >> 16)) * bias0);
;       float z2 = xa[2] * (acc[bb][4 * g + 2] * inv0 + bf2f((bf16_t)(vv.y & 0xffff)) * bias0);
;       float z3 = xa[3] * (acc[bb][4 * g + 3] * inv0 + bf2f((bf16_t)(vv.y >> 16)) * bias0);
;       uint2 o; o.x = pack2(z0, z1); o.y = pack2(z2, z3);
;       *zp = o;
;     }
	v_lshlrev_b32_e32 v116, 16, v68
	v_and_b32_e32 v117, 0xffff0000, v68
	v_lshlrev_b32_e32 v68, 16, v69
	v_and_b32_e32 v69, 0xffff0000, v69
	v_pk_mul_f32 v[68:69], v[102:103], v[68:69] op_sel_hi:[0,1]
	v_pk_fma_f32 v[58:59], v[104:105], v[58:59], v[68:69] op_sel_hi:[0,1,1]
	v_add_u32_e32 v112, 0x4000, v107
	s_waitcnt vmcnt(2)
	v_lshlrev_b32_e32 v115, 16, v49
	v_and_b32_e32 v114, 0xffff0000, v48
	v_and_b32_e32 v49, 0xffff0000, v49
	s_waitcnt vmcnt(1)
	v_lshlrev_b32_e32 v110, 16, v110
	s_waitcnt vmcnt(0)
	v_lshlrev_b32_e32 v54, 16, v54
	v_cndmask_b32_e64 v75, 0, v54, s[42:43]
	v_lshlrev_b32_e32 v54, 16, v48
	v_mov_b32_e32 v48, v115
	v_pk_mul_f32 v[118:119], v[92:93], v[48:49] op_sel_hi:[0,1]
	v_pk_fma_f32 v[118:119], v[96:97], v[114:115], v[118:119] op_sel_hi:[0,1,1]
	v_mov_b32_e32 v74, v49
	v_cndmask_b32_e64 v111, 0, v110, s[40:41]
	v_pk_fma_f32 v[48:49], v[90:91], v[74:75], v[118:119] op_sel_hi:[0,1,1]
	v_pk_mul_f32 v[74:75], v[102:103], v[116:117] op_sel_hi:[0,1]
	v_mov_b32_e32 v110, v114
	v_pk_fma_f32 v[56:57], v[104:105], v[56:57], v[74:75] op_sel_hi:[0,1,1]
	v_pk_mul_f32 v[74:75], v[92:93], v[110:111]
	v_pk_add_f32 v[48:49], v[94:95], v[48:49] op_sel_hi:[0,1]
	v_pk_fma_f32 v[74:75], v[92:93], v[54:55], v[74:75] op_sel:[0,0,1] op_sel_hi:[1,0,0]
	v_cvt_pk_bf16_f32 v48, v48, v49
	v_pk_fma_f32 v[74:75], v[90:91], v[114:115], v[74:75] op_sel_hi:[0,1,1]
	v_pk_add_f32 v[74:75], v[94:95], v[74:75] op_sel_hi:[0,1]
	v_cvt_pk_bf16_f32 v54, v74, v75
	v_and_b32_e32 v49, 0xffff0000, v48
	v_lshlrev_b32_e32 v48, 16, v48
	v_and_b32_e32 v75, 0xffff0000, v54
	v_lshlrev_b32_e32 v74, 16, v54
	v_pk_mul_f32 v[56:57], v[56:57], v[74:75]
	v_pk_mul_f32 v[48:49], v[58:59], v[48:49]
	v_or_b32_e32 v74, 24, v100
	v_cvt_pk_bf16_f32 v56, v56, v57
	v_cvt_pk_bf16_f32 v57, v48, v49
	v_max_i32_e32 v48, 1, v74
	v_lshlrev_b32_e32 v54, 1, v48
	v_min_i32_e32 v48, 0xffb, v74
	v_ashrrev_i32_e32 v49, 31, v48
	global_load_dwordx2 v[58:59], v[108:109], off offset:48
	global_load_ushort v75, v54, s[0:1] offset:-2
	v_lshlrev_b64 v[48:49], 1, v[48:49]
	v_lshl_add_u64 v[68:69], s[0:1], 0, v[48:49]
	global_load_ushort v68, v[68:69], off offset:8
	v_cmp_gt_i32_e64 s[38:39], s38, v74
	v_cmp_lt_i32_e64 s[36:37], 0, v74
	v_lshlrev_b32_e32 v114, 16, v70
	v_and_b32_e32 v115, 0xffff0000, v70
	s_or_b32 s0, vcc_lo, 0x900
	v_lshlrev_b32_e32 v70, 16, v71
	v_and_b32_e32 v71, 0xffff0000, v71
	s_add_u32 s0, s0, s12
	s_addc_u32 s1, 0, s13
	s_lshl_b64 s[0:1], s[0:1], 13
	s_add_u32 s0, s8, s0
	s_addc_u32 s1, s9, s1
	s_waitcnt vmcnt(2)
	v_lshlrev_b32_e32 v111, 16, v59
	v_lshlrev_b32_e32 v108, 16, v58
	v_and_b32_e32 v110, 0xffff0000, v58
	v_and_b32_e32 v59, 0xffff0000, v59
	v_mov_b32_e32 v58, v111
	s_waitcnt vmcnt(0)
	v_lshlrev_b32_e32 v68, 16, v68
	v_pk_mul_f32 v[116:117], v[92:93], v[58:59] op_sel_hi:[0,1]
	v_lshlrev_b32_e32 v75, 16, v75
	v_cndmask_b32_e64 v69, 0, v68, s[38:39]
	v_pk_fma_f32 v[116:117], v[96:97], v[110:111], v[116:117] op_sel_hi:[0,1,1]
	v_mov_b32_e32 v68, v59
	v_cndmask_b32_e64 v75, 0, v75, s[36:37]
	v_pk_fma_f32 v[58:59], v[90:91], v[68:69], v[116:117] op_sel_hi:[0,1,1]
	v_pk_mul_f32 v[68:69], v[102:103], v[114:115] op_sel_hi:[0,1]
	v_mov_b32_e32 v74, v110
	v_pk_fma_f32 v[60:61], v[104:105], v[60:61], v[68:69] op_sel_hi:[0,1,1]
	v_pk_mul_f32 v[68:69], v[92:93], v[74:75]
	v_pk_add_f32 v[58:59], v[94:95], v[58:59] op_sel_hi:[0,1]
	v_pk_fma_f32 v[68:69], v[92:93], v[108:109], v[68:69] op_sel:[0,0,1] op_sel_hi:[1,0,0]
	v_cvt_pk_bf16_f32 v58, v58, v59
	v_pk_fma_f32 v[68:69], v[90:91], v[110:111], v[68:69] op_sel_hi:[0,1,1]
	v_pk_add_f32 v[68:69], v[94:95], v[68:69] op_sel_hi:[0,1]
	v_cvt_pk_bf16_f32 v68, v68, v69
	v_and_b32_e32 v69, 0xffff0000, v68
	v_lshlrev_b32_e32 v68, 16, v68
	v_pk_mul_f32 v[60:61], v[60:61], v[68:69]
	v_pk_mul_f32 v[68:69], v[102:103], v[70:71] op_sel_hi:[0,1]
	v_and_b32_e32 v59, 0xffff0000, v58
	v_lshlrev_b32_e32 v58, 16, v58
	v_pk_fma_f32 v[62:63], v[104:105], v[62:63], v[68:69] op_sel_hi:[0,1,1]
	v_pk_mul_f32 v[58:59], v[62:63], v[58:59]
	v_cvt_pk_bf16_f32 v60, v60, v61
	v_cvt_pk_bf16_f32 v61, v58, v59
	ds_write2_b64 v89, v[56:57], v[60:61] offset0:68 offset1:70
	v_lshl_add_u64 v[56:57], s[0:1], 0, v[76:77]
	global_load_dwordx2 v[56:57], v[56:57], off
	v_lshl_add_u64 v[58:59], s[0:1], 0, v[78:79]
	global_load_ushort v58, v[58:59], off offset:8
	v_add_u32_e32 v114, 0x8000, v107
	global_load_ushort v60, v81, s[0:1] offset:-2
	v_add_u32_e32 v115, 0xb800, v107
	s_waitcnt vmcnt(2)
	v_lshlrev_b32_e32 v71, 16, v57
	v_and_b32_e32 v75, 0xffff0000, v57
	v_mov_b32_e32 v74, v71
	s_waitcnt vmcnt(1)
	v_lshlrev_b32_e32 v58, 16, v58
	v_and_b32_e32 v70, 0xffff0000, v56
	v_pk_mul_f32 v[110:111], v[92:93], v[74:75] op_sel_hi:[0,1]
	v_cndmask_b32_e64 v63, 0, v58, s[48:49]
	v_pk_fma_f32 v[110:111], v[96:97], v[70:71], v[110:111] op_sel_hi:[0,1,1]
	v_mov_b32_e32 v62, v75
	v_pk_fma_f32 v[62:63], v[90:91], v[62:63], v[110:111] op_sel_hi:[0,1,1]
	s_waitcnt vmcnt(0)
	v_lshlrev_b32_e32 v60, 16, v60
	v_pk_add_f32 v[62:63], v[94:95], v[62:63] op_sel_hi:[0,1]
	v_cndmask_b32_e64 v61, 0, v60, s[50:51]
	v_lshlrev_b32_e32 v68, 16, v56
	ds_read2_b64 v[56:59], v112 offset0:192 offset1:194
	v_cvt_pk_bf16_f32 v60, v62, v63
	v_and_b32_e32 v63, 0xffff0000, v60
	v_lshlrev_b32_e32 v62, 16, v60
	v_mov_b32_e32 v60, v70
	v_pk_mul_f32 v[60:61], v[92:93], v[60:61]
	s_waitcnt lgkmcnt(0)
; DI unsigned pack2(float lo, float hi) { f32x2_t v = {lo, hi}; bf16x2_t r = __builtin_convertvector(v, bf16x2_t); return __builtin_bit_cast(unsigned, r); }
; DI bf16_t f2bf(float x) { return (bf16_t)(pack2(x, x) & 0xffffu); }
; DI float bf2f(bf16_t v) { return __uint_as_float(((unsigned)v) << 16); }
; DI float rbf(float x) { return bf2f(f2bf(x)); }
; DI void hy_conv4(const HyRaw4& r, int t0, float w0, float w1, float w2, float wb, float (&o)[4]) {
;   const float xm = t0 > 0 ? bf2f(r.m) : 0.f, xp = t0 + 4 < SEQ ? bf2f(r.pz) : 0.f;
;   const float e0 = bf2f((bf16_t)(r.v.x & 0xffff)), e1 = bf2f((bf16_t)(r.v.x >> 16)), e2 = bf2f((bf16_t)(r.v.y & 0xffff)), e3 = bf2f((bf16_t)(r.v.y >> 16));
;   o[0] = rbf(xm * w0 + e0 * w1 + e1 * w2 + wb);
;   o[1] = rbf(e0 * w0 + e1 * w1 + e2 * w2 + wb);
;   o[2] = rbf(e1 * w0 + e2 * w1 + e3 * w2 + wb);
;   o[3] = rbf(e2 * w0 + e3 * w1 + xp * w2 + wb);
; }
; DI void hyena_item(const Params& p, int layer, int c, int bh, char* smem) {
;     ...
;   for (int bb = 0; bb < 4; ++bb) {
;     const bf16_t* x1 = HT + (((size_t)1 * NB + bh * 4 + bb) * 256 + c) * SEQ;
;     bf16_t* zw = sZ + bb * ZROW;
; #pragma unroll
;     for (int g = 0; g < 4; ++g) {
;       const int off = 8 * g + 4 * h;
;       float xa[4];
;       hy_conv4(hy_raw4(x1, i * 32 + off), i * 32 + off, aw0, aw1, aw2, awb, xa);
;       uint2* zp = (uint2*)(zw + (i + 32) * ZB + off);
;       uint2 vv = *zp;
;       float z0 = xa[0] * (acc[bb][4 * g + 0] * inv0 + bf2f((bf16_t)(vv.x & 0xffff)) * bias0);
;       float z1 = xa[1] * (acc[bb][4 * g + 1] * inv0 + bf2f((bf16_t)(vv.x >> 16)) * bias0);
;       float z2 = xa[2] * (acc[bb][4 * g + 2] * inv0 + bf2f((bf16_t)(vv.y & 0xffff)) * bias0);
;       float z3 = xa[3] * (acc[bb][4 * g + 3] * inv0 + bf2f((bf16_t)(vv.y >> 16)) * bias0);
;       uint2 o; o.x = pack2(z0, z1); o.y = pack2(z2, z3);
;       *zp = o;
;     }
	v_lshlrev_b32_e32 v108, 16, v56
	v_pk_fma_f32 v[60:61], v[92:93], v[68:69], v[60:61] op_sel:[0,0,1] op_sel_hi:[1,0,0]
	v_and_b32_e32 v109, 0xffff0000, v56
	v_pk_fma_f32 v[60:61], v[90:91], v[70:71], v[60:61] op_sel_hi:[0,1,1]
	v_lshlrev_b32_e32 v56, 16, v57
	v_and_b32_e32 v57, 0xffff0000, v57
	v_pk_add_f32 v[60:61], v[94:95], v[60:61] op_sel_hi:[0,1]
	v_pk_mul_f32 v[74:75], v[102:103], v[108:109] op_sel_hi:[0,1]
	v_cvt_pk_bf16_f32 v60, v60, v61
	v_pk_mul_f32 v[56:57], v[102:103], v[56:57] op_sel_hi:[0,1]
	v_pk_fma_f32 v[32:33], v[104:105], v[32:33], v[74:75] op_sel_hi:[0,1,1]
	v_and_b32_e32 v61, 0xffff0000, v60
	v_lshlrev_b32_e32 v60, 16, v60
	v_pk_fma_f32 v[34:35], v[104:105], v[34:35], v[56:57] op_sel_hi:[0,1,1]
	v_pk_mul_f32 v[32:33], v[32:33], v[60:61]
	v_pk_mul_f32 v[34:35], v[34:35], v[62:63]
	v_lshl_add_u64 v[56:57], s[0:1], 0, v[50:51]
	v_cvt_pk_bf16_f32 v32, v32, v33
	v_cvt_pk_bf16_f32 v33, v34, v35
	global_load_dwordx2 v[34:35], v[56:57], off offset:16
	v_lshl_add_u64 v[60:61], s[0:1], 0, v[72:73]
	global_load_ushort v60, v[60:61], off offset:8
	v_lshlrev_b32_e32 v74, 16, v58
	global_load_ushort v62, v101, s[0:1] offset:-2
	v_and_b32_e32 v75, 0xffff0000, v58
	v_lshlrev_b32_e32 v58, 16, v59
	v_and_b32_e32 v59, 0xffff0000, v59
	v_pk_mul_f32 v[58:59], v[102:103], v[58:59] op_sel_hi:[0,1]
	v_pk_fma_f32 v[38:39], v[104:105], v[38:39], v[58:59] op_sel_hi:[0,1,1]
	s_waitcnt vmcnt(2)
	v_lshlrev_b32_e32 v71, 16, v35
	v_lshlrev_b32_e32 v68, 16, v34
	v_and_b32_e32 v70, 0xffff0000, v34
	v_and_b32_e32 v35, 0xffff0000, v35
	v_mov_b32_e32 v34, v71
	s_waitcnt vmcnt(1)
	v_lshlrev_b32_e32 v60, 16, v60
	v_pk_mul_f32 v[108:109], v[92:93], v[34:35] op_sel_hi:[0,1]
	s_waitcnt vmcnt(0)
	v_lshlrev_b32_e32 v62, 16, v62
	v_cndmask_b32_e64 v61, 0, v60, s[46:47]
	v_pk_fma_f32 v[108:109], v[96:97], v[70:71], v[108:109] op_sel_hi:[0,1,1]
	v_mov_b32_e32 v60, v35
	v_cndmask_b32_e64 v63, 0, v62, s[44:45]
	v_pk_fma_f32 v[34:35], v[90:91], v[60:61], v[108:109] op_sel_hi:[0,1,1]
	v_pk_mul_f32 v[60:61], v[102:103], v[74:75] op_sel_hi:[0,1]
	v_mov_b32_e32 v62, v70
	v_pk_fma_f32 v[36:37], v[104:105], v[36:37], v[60:61] op_sel_hi:[0,1,1]
	v_pk_mul_f32 v[60:61], v[92:93], v[62:63]
	v_pk_add_f32 v[34:35], v[94:95], v[34:35] op_sel_hi:[0,1]
	v_pk_fma_f32 v[60:61], v[92:93], v[68:69], v[60:61] op_sel:[0,0,1] op_sel_hi:[1,0,0]
	v_cvt_pk_bf16_f32 v34, v34, v35
	v_pk_fma_f32 v[60:61], v[90:91], v[70:71], v[60:61] op_sel_hi:[0,1,1]
	v_pk_add_f32 v[60:61], v[94:95], v[60:61] op_sel_hi:[0,1]
	v_cvt_pk_bf16_f32 v60, v60, v61
	v_and_b32_e32 v35, 0xffff0000, v34
	v_lshlrev_b32_e32 v34, 16, v34
	v_and_b32_e32 v61, 0xffff0000, v60
	v_lshlrev_b32_e32 v60, 16, v60
	v_pk_mul_f32 v[36:37], v[36:37], v[60:61]
	v_pk_mul_f32 v[34:35], v[38:39], v[34:35]
	v_cvt_pk_bf16_f32 v36, v36, v37
	v_cvt_pk_bf16_f32 v37, v34, v35
	ds_write2_b64 v112, v[32:33], v[36:37] offset0:192 offset1:194
	global_load_dwordx2 v[32:33], v[56:57], off offset:32
	global_load_ushort v36, v55, s[0:1] offset:-2
	v_lshl_add_u64 v[34:35], s[0:1], 0, v[52:53]
	global_load_ushort v34, v[34:35], off offset:8
	s_waitcnt vmcnt(2)
	v_lshlrev_b32_e32 v61, 16, v33
	v_and_b32_e32 v63, 0xffff0000, v33
	v_mov_b32_e32 v62, v61
	s_waitcnt vmcnt(0)
	v_lshlrev_b32_e32 v34, 16, v34
	v_and_b32_e32 v60, 0xffff0000, v32
	v_pk_mul_f32 v[70:71], v[92:93], v[62:63] op_sel_hi:[0,1]
	v_cndmask_b32_e64 v39, 0, v34, s[42:43]
	v_pk_fma_f32 v[70:71], v[96:97], v[60:61], v[70:71] op_sel_hi:[0,1,1]
	v_mov_b32_e32 v38, v63
	v_pk_fma_f32 v[38:39], v[90:91], v[38:39], v[70:71] op_sel_hi:[0,1,1]
	v_lshlrev_b32_e32 v36, 16, v36
	v_pk_add_f32 v[38:39], v[94:95], v[38:39] op_sel_hi:[0,1]
	v_cndmask_b32_e64 v37, 0, v36, s[40:41]
	v_lshlrev_b32_e32 v58, 16, v32
	ds_read2_b64 v[32:35], v112 offset0:196 offset1:198
	v_cvt_pk_bf16_f32 v36, v38, v39
	v_and_b32_e32 v39, 0xffff0000, v36
	v_lshlrev_b32_e32 v38, 16, v36
	v_mov_b32_e32 v36, v60
	v_pk_mul_f32 v[36:37], v[92:93], v[36:37]
	s_waitcnt lgkmcnt(0)
	v_lshlrev_b32_e32 v68, 16, v32
	v_pk_fma_f32 v[36:37], v[92:93], v[58:59], v[36:37] op_sel:[0,0,1] op_sel_hi:[1,0,0]
	v_and_b32_e32 v69, 0xffff0000, v32
	v_pk_fma_f32 v[36:37], v[90:91], v[60:61], v[36:37] op_sel_hi:[0,1,1]
	v_lshlrev_b32_e32 v32, 16, v33
	v_and_b32_e32 v33, 0xffff0000, v33
	v_pk_add_f32 v[36:37], v[94:95], v[36:37] op_sel_hi:[0,1]
	v_pk_mul_f32 v[62:63], v[102:103], v[68:69] op_sel_hi:[0,1]
	v_cvt_pk_bf16_f32 v36, v36, v37
	v_pk_mul_f32 v[32:33], v[102:103], v[32:33] op_sel_hi:[0,1]
	v_pk_fma_f32 v[40:41], v[104:105], v[40:41], v[62:63] op_sel_hi:[0,1,1]
	v_and_b32_e32 v37, 0xffff0000, v36
	v_lshlrev_b32_e32 v36, 16, v36
	v_pk_fma_f32 v[32:33], v[104:105], v[42:43], v[32:33] op_sel_hi:[0,1,1]
	v_pk_mul_f32 v[36:37], v[40:41], v[36:37]
	v_pk_mul_f32 v[32:33], v[32:33], v[38:39]
	v_cvt_pk_bf16_f32 v36, v36, v37
	v_cvt_pk_bf16_f32 v37, v32, v33
	global_load_dwordx2 v[32:33], v[56:57], off offset:48
	global_load_ushort v40, v54, s[0:1] offset:-2
	v_lshl_add_u64 v[38:39], s[0:1], 0, v[48:49]
	global_load_ushort v38, v[38:39], off offset:8
	s_or_b32 s0, vcc_lo, 0xa00
	s_add_u32 s0, s0, s12
	v_lshlrev_b32_e32 v58, 16, v34
	v_and_b32_e32 v59, 0xffff0000, v34
	v_lshlrev_b32_e32 v34, 16, v35
	v_and_b32_e32 v35, 0xffff0000, v35
	s_addc_u32 s1, 0, s13
	v_pk_mul_f32 v[34:35], v[102:103], v[34:35] op_sel_hi:[0,1]
	s_lshl_b64 s[0:1], s[0:1], 13
	v_pk_fma_f32 v[34:35], v[104:105], v[46:47], v[34:35] op_sel_hi:[0,1,1]
	s_add_u32 s0, s8, s0
	s_addc_u32 s1, s9, s1
	v_mov_b32_e32 v63, 0
	v_mov_b32_e32 v62, v63
	s_waitcnt vmcnt(2)
	v_lshlrev_b32_e32 v57, 16, v33
	s_waitcnt vmcnt(1)
; DI unsigned pack2(float lo, float hi) { f32x2_t v = {lo, hi}; bf16x2_t r = __builtin_convertvector(v, bf16x2_t); return __builtin_bit_cast(unsigned, r); }
; DI bf16_t f2bf(float x) { return (bf16_t)(pack2(x, x) & 0xffffu); }
; DI float bf2f(bf16_t v) { return __uint_as_float(((unsigned)v) << 16); }
; DI float rbf(float x) { return bf2f(f2bf(x)); }
; DI void hy_conv4(const HyRaw4& r, int t0, float w0, float w1, float w2, float wb, float (&o)[4]) {
;   const float xm = t0 > 0 ? bf2f(r.m) : 0.f, xp = t0 + 4 < SEQ ? bf2f(r.pz) : 0.f;
;   const float e0 = bf2f((bf16_t)(r.v.x & 0xffff)), e1 = bf2f((bf16_t)(r.v.x >> 16)), e2 = bf2f((bf16_t)(r.v.y & 0xffff)), e3 = bf2f((bf16_t)(r.v.y >> 16));
;   o[0] = rbf(xm * w0 + e0 * w1 + e1 * w2 + wb);
;   o[1] = rbf(e0 * w0 + e1 * w1 + e2 * w2 + wb);
;   o[2] = rbf(e1 * w0 + e2 * w1 + e3 * w2 + wb);
;   o[3] = rbf(e2 * w0 + e3 * w1 + xp * w2 + wb);
; }
; DI void hyena_item(const Params& p, int layer, int c, int bh, char* smem) {
;     ...
;   for (int bb = 0; bb < 4; ++bb) {
;     const bf16_t* x1 = HT + (((size_t)1 * NB + bh * 4 + bb) * 256 + c) * SEQ;
;     bf16_t* zw = sZ + bb * ZROW;
; #pragma unroll
;     for (int g = 0; g < 4; ++g) {
;       const int off = 8 * g + 4 * h;
;       float xa[4];
;       hy_conv4(hy_raw4(x1, i * 32 + off), i * 32 + off, aw0, aw1, aw2, awb, xa);
;       uint2* zp = (uint2*)(zw + (i + 32) * ZB + off);
;       uint2 vv = *zp;
;       float z0 = xa[0] * (acc[bb][4 * g + 0] * inv0 + bf2f((bf16_t)(vv.x & 0xffff)) * bias0);
;       float z1 = xa[1] * (acc[bb][4 * g + 1] * inv0 + bf2f((bf16_t)(vv.x >> 16)) * bias0);
;       float z2 = xa[2] * (acc[bb][4 * g + 2] * inv0 + bf2f((bf16_t)(vv.y & 0xffff)) * bias0);
;       float z3 = xa[3] * (acc[bb][4 * g + 3] * inv0 + bf2f((bf16_t)(vv.y >> 16)) * bias0);
;       uint2 o; o.x = pack2(z0, z1); o.y = pack2(z2, z3);
;       *zp = o;
;     }
	v_lshlrev_b32_e32 v40, 16, v40
	v_lshlrev_b32_e32 v42, 16, v32
	v_and_b32_e32 v56, 0xffff0000, v32
	v_and_b32_e32 v33, 0xffff0000, v33
	v_mov_b32_e32 v32, v57
	v_cndmask_b32_e64 v41, 0, v40, s[36:37]
	s_waitcnt vmcnt(0)
	v_lshlrev_b32_e32 v38, 16, v38
	v_pk_mul_f32 v[60:61], v[92:93], v[32:33] op_sel_hi:[0,1]
	v_mov_b32_e32 v40, v56
	v_cndmask_b32_e64 v39, 0, v38, s[38:39]
	v_pk_fma_f32 v[60:61], v[96:97], v[56:57], v[60:61] op_sel_hi:[0,1,1]
	v_mov_b32_e32 v38, v33
	v_pk_mul_f32 v[40:41], v[92:93], v[40:41]
	v_pk_fma_f32 v[32:33], v[90:91], v[38:39], v[60:61] op_sel_hi:[0,1,1]
	v_pk_fma_f32 v[40:41], v[92:93], v[42:43], v[40:41] op_sel:[0,0,1] op_sel_hi:[1,0,0]
	v_pk_add_f32 v[32:33], v[94:95], v[32:33] op_sel_hi:[0,1]
	v_pk_fma_f32 v[40:41], v[90:91], v[56:57], v[40:41] op_sel_hi:[0,1,1]
	v_cvt_pk_bf16_f32 v32, v32, v33
	v_pk_add_f32 v[40:41], v[94:95], v[40:41] op_sel_hi:[0,1]
	v_and_b32_e32 v33, 0xffff0000, v32
	v_lshlrev_b32_e32 v32, 16, v32
	v_pk_mul_f32 v[38:39], v[102:103], v[58:59] op_sel_hi:[0,1]
	v_cvt_pk_bf16_f32 v40, v40, v41
	v_pk_fma_f32 v[38:39], v[104:105], v[44:45], v[38:39] op_sel_hi:[0,1,1]
	v_and_b32_e32 v41, 0xffff0000, v40
	v_lshlrev_b32_e32 v40, 16, v40
	v_pk_mul_f32 v[32:33], v[34:35], v[32:33]
	v_pk_mul_f32 v[38:39], v[38:39], v[40:41]
	v_cvt_pk_bf16_f32 v35, v32, v33
	v_lshl_add_u64 v[32:33], s[0:1], 0, v[76:77]
	v_cvt_pk_bf16_f32 v34, v38, v39
	global_load_dwordx2 v[32:33], v[32:33], off
	ds_write2_b64 v112, v[36:37], v[34:35] offset0:196 offset1:198
	v_lshl_add_u64 v[34:35], s[0:1], 0, v[78:79]
	global_load_ushort v34, v[34:35], off offset:8
	v_mov_b32_e32 v61, v63
	global_load_ushort v36, v81, s[0:1] offset:-2
	v_mov_b32_e32 v60, v63
	v_mov_b32_e32 v59, v63
	v_mov_b32_e32 v58, v63
	s_waitcnt vmcnt(2)
	v_lshlrev_b32_e32 v43, 16, v33
	v_and_b32_e32 v45, 0xffff0000, v33
	v_mov_b32_e32 v44, v43
	s_waitcnt vmcnt(1)
	v_lshlrev_b32_e32 v34, 16, v34
	v_and_b32_e32 v42, 0xffff0000, v32
	v_pk_mul_f32 v[56:57], v[92:93], v[44:45] op_sel_hi:[0,1]
	v_cndmask_b32_e64 v39, 0, v34, s[48:49]
	v_pk_fma_f32 v[56:57], v[96:97], v[42:43], v[56:57] op_sel_hi:[0,1,1]
	v_mov_b32_e32 v38, v45
	v_pk_fma_f32 v[38:39], v[90:91], v[38:39], v[56:57] op_sel_hi:[0,1,1]
	s_waitcnt vmcnt(0)
	v_lshlrev_b32_e32 v36, 16, v36
	v_pk_add_f32 v[38:39], v[94:95], v[38:39] op_sel_hi:[0,1]
	v_cndmask_b32_e64 v37, 0, v36, s[50:51]
	v_lshlrev_b32_e32 v40, 16, v32
	ds_read2_b64 v[32:35], v114 offset0:64 offset1:66
	v_cvt_pk_bf16_f32 v36, v38, v39
	v_and_b32_e32 v39, 0xffff0000, v36
	v_lshlrev_b32_e32 v38, 16, v36
	v_mov_b32_e32 v36, v42
	v_pk_mul_f32 v[36:37], v[92:93], v[36:37]
	s_waitcnt lgkmcnt(0)
	v_lshlrev_b32_e32 v46, 16, v32
	v_pk_fma_f32 v[36:37], v[92:93], v[40:41], v[36:37] op_sel:[0,0,1] op_sel_hi:[1,0,0]
	v_and_b32_e32 v47, 0xffff0000, v32
	v_pk_fma_f32 v[36:37], v[90:91], v[42:43], v[36:37] op_sel_hi:[0,1,1]
	v_lshlrev_b32_e32 v32, 16, v33
	v_and_b32_e32 v33, 0xffff0000, v33
	v_pk_add_f32 v[36:37], v[94:95], v[36:37] op_sel_hi:[0,1]
	v_pk_mul_f32 v[44:45], v[102:103], v[46:47] op_sel_hi:[0,1]
	v_cvt_pk_bf16_f32 v36, v36, v37
	v_pk_mul_f32 v[32:33], v[102:103], v[32:33] op_sel_hi:[0,1]
	v_pk_fma_f32 v[16:17], v[104:105], v[16:17], v[44:45] op_sel_hi:[0,1,1]
	v_and_b32_e32 v37, 0xffff0000, v36
	v_lshlrev_b32_e32 v36, 16, v36
	v_pk_fma_f32 v[18:19], v[104:105], v[18:19], v[32:33] op_sel_hi:[0,1,1]
	v_pk_mul_f32 v[16:17], v[16:17], v[36:37]
	v_pk_mul_f32 v[18:19], v[18:19], v[38:39]
	v_lshl_add_u64 v[32:33], s[0:1], 0, v[50:51]
	v_cvt_pk_bf16_f32 v16, v16, v17
	v_cvt_pk_bf16_f32 v17, v18, v19
	global_load_dwordx2 v[18:19], v[32:33], off offset:16
	v_lshl_add_u64 v[36:37], s[0:1], 0, v[72:73]
	global_load_ushort v36, v[36:37], off offset:8
	v_lshlrev_b32_e32 v44, 16, v34
	global_load_ushort v38, v101, s[0:1] offset:-2
	v_and_b32_e32 v45, 0xffff0000, v34
	v_lshlrev_b32_e32 v34, 16, v35
	v_and_b32_e32 v35, 0xffff0000, v35
	v_pk_mul_f32 v[34:35], v[102:103], v[34:35] op_sel_hi:[0,1]
	v_pk_fma_f32 v[22:23], v[104:105], v[22:23], v[34:35] op_sel_hi:[0,1,1]
	v_mov_b32_e32 v57, v63
	v_mov_b32_e32 v56, v63
	s_waitcnt vmcnt(2)
	v_lshlrev_b32_e32 v43, 16, v19
	v_lshlrev_b32_e32 v40, 16, v18
	v_and_b32_e32 v42, 0xffff0000, v18
	v_and_b32_e32 v19, 0xffff0000, v19
	v_mov_b32_e32 v18, v43
	s_waitcnt vmcnt(1)
	v_lshlrev_b32_e32 v36, 16, v36
	v_pk_mul_f32 v[46:47], v[92:93], v[18:19] op_sel_hi:[0,1]
	s_waitcnt vmcnt(0)
	v_lshlrev_b32_e32 v38, 16, v38
	v_cndmask_b32_e64 v37, 0, v36, s[46:47]
	v_pk_fma_f32 v[46:47], v[96:97], v[42:43], v[46:47] op_sel_hi:[0,1,1]
	v_mov_b32_e32 v36, v19
	v_cndmask_b32_e64 v39, 0, v38, s[44:45]
	v_pk_fma_f32 v[18:19], v[90:91], v[36:37], v[46:47] op_sel_hi:[0,1,1]
	v_pk_mul_f32 v[36:37], v[102:103], v[44:45] op_sel_hi:[0,1]
	v_mov_b32_e32 v38, v42
	v_pk_fma_f32 v[20:21], v[104:105], v[20:21], v[36:37] op_sel_hi:[0,1,1]
	v_pk_mul_f32 v[36:37], v[92:93], v[38:39]
	v_pk_add_f32 v[18:19], v[94:95], v[18:19] op_sel_hi:[0,1]
	v_pk_fma_f32 v[36:37], v[92:93], v[40:41], v[36:37] op_sel:[0,0,1] op_sel_hi:[1,0,0]
	v_cvt_pk_bf16_f32 v18, v18, v19
	v_pk_fma_f32 v[36:37], v[90:91], v[42:43], v[36:37] op_sel_hi:[0,1,1]
	v_pk_add_f32 v[36:37], v[94:95], v[36:37] op_sel_hi:[0,1]
	v_cvt_pk_bf16_f32 v36, v36, v37
	v_and_b32_e32 v19, 0xffff0000, v18
	v_lshlrev_b32_e32 v18, 16, v18
	v_and_b32_e32 v37, 0xffff0000, v36
	v_lshlrev_b32_e32 v36, 16, v36
	v_pk_mul_f32 v[20:21], v[20:21], v[36:37]
	v_pk_mul_f32 v[18:19], v[22:23], v[18:19]
	v_cvt_pk_bf16_f32 v20, v20, v21
	v_cvt_pk_bf16_f32 v21, v18, v19
	ds_write2_b64 v114, v[16:17], v[20:21] offset0:64 offset1:66
	global_load_dwordx2 v[16:17], v[32:33], off offset:32
	global_load_ushort v20, v55, s[0:1] offset:-2
	v_lshl_add_u64 v[18:19], s[0:1], 0, v[52:53]
	global_load_ushort v18, v[18:19], off offset:8
	v_mov_b32_e32 v47, v63
	v_mov_b32_e32 v46, v63
	v_mov_b32_e32 v45, v63
	v_mov_b32_e32 v44, v63
	s_waitcnt vmcnt(2)
; DI unsigned pack2(float lo, float hi) { f32x2_t v = {lo, hi}; bf16x2_t r = __builtin_convertvector(v, bf16x2_t); return __builtin_bit_cast(unsigned, r); }
; DI bf16_t f2bf(float x) { return (bf16_t)(pack2(x, x) & 0xffffu); }
; DI float bf2f(bf16_t v) { return __uint_as_float(((unsigned)v) << 16); }
; DI float rbf(float x) { return bf2f(f2bf(x)); }
; DI void hy_conv4(const HyRaw4& r, int t0, float w0, float w1, float w2, float wb, float (&o)[4]) {
;   const float xm = t0 > 0 ? bf2f(r.m) : 0.f, xp = t0 + 4 < SEQ ? bf2f(r.pz) : 0.f;
;   const float e0 = bf2f((bf16_t)(r.v.x & 0xffff)), e1 = bf2f((bf16_t)(r.v.x >> 16)), e2 = bf2f((bf16_t)(r.v.y & 0xffff)), e3 = bf2f((bf16_t)(r.v.y >> 16));
;   o[0] = rbf(xm * w0 + e0 * w1 + e1 * w2 + wb);
;   o[1] = rbf(e0 * w0 + e1 * w1 + e2 * w2 + wb);
;   o[2] = rbf(e1 * w0 + e2 * w1 + e3 * w2 + wb);
;   o[3] = rbf(e2 * w0 + e3 * w1 + xp * w2 + wb);
; }
; DI void hyena_item(const Params& p, int layer, int c, int bh, char* smem) {
;     ...
;   for (int bb = 0; bb < 4; ++bb) {
;     const bf16_t* x1 = HT + (((size_t)1 * NB + bh * 4 + bb) * 256 + c) * SEQ;
;     bf16_t* zw = sZ + bb * ZROW;
; #pragma unroll
;     for (int g = 0; g < 4; ++g) {
;       const int off = 8 * g + 4 * h;
;       float xa[4];
;       hy_conv4(hy_raw4(x1, i * 32 + off), i * 32 + off, aw0, aw1, aw2, awb, xa);
;       uint2* zp = (uint2*)(zw + (i + 32) * ZB + off);
;       uint2 vv = *zp;
;       float z0 = xa[0] * (acc[bb][4 * g + 0] * inv0 + bf2f((bf16_t)(vv.x & 0xffff)) * bias0);
;       float z1 = xa[1] * (acc[bb][4 * g + 1] * inv0 + bf2f((bf16_t)(vv.x >> 16)) * bias0);
;       float z2 = xa[2] * (acc[bb][4 * g + 2] * inv0 + bf2f((bf16_t)(vv.y & 0xffff)) * bias0);
;       float z3 = xa[3] * (acc[bb][4 * g + 3] * inv0 + bf2f((bf16_t)(vv.y >> 16)) * bias0);
;       uint2 o; o.x = pack2(z0, z1); o.y = pack2(z2, z3);
;       *zp = o;
;     }
	v_lshlrev_b32_e32 v37, 16, v17
	v_and_b32_e32 v39, 0xffff0000, v17
	v_mov_b32_e32 v38, v37
	s_waitcnt vmcnt(0)
	v_lshlrev_b32_e32 v18, 16, v18
	v_and_b32_e32 v36, 0xffff0000, v16
	v_pk_mul_f32 v[42:43], v[92:93], v[38:39] op_sel_hi:[0,1]
	v_cndmask_b32_e64 v23, 0, v18, s[42:43]
	v_pk_fma_f32 v[42:43], v[96:97], v[36:37], v[42:43] op_sel_hi:[0,1,1]
	v_mov_b32_e32 v22, v39
	v_pk_fma_f32 v[22:23], v[90:91], v[22:23], v[42:43] op_sel_hi:[0,1,1]
	v_lshlrev_b32_e32 v20, 16, v20
	v_pk_add_f32 v[22:23], v[94:95], v[22:23] op_sel_hi:[0,1]
	v_cndmask_b32_e64 v21, 0, v20, s[40:41]
	v_lshlrev_b32_e32 v34, 16, v16
	ds_read2_b64 v[16:19], v114 offset0:68 offset1:70
	v_cvt_pk_bf16_f32 v20, v22, v23
	v_and_b32_e32 v23, 0xffff0000, v20
	v_lshlrev_b32_e32 v22, 16, v20
	v_mov_b32_e32 v20, v36
	v_pk_mul_f32 v[20:21], v[92:93], v[20:21]
	s_waitcnt lgkmcnt(0)
	v_lshlrev_b32_e32 v40, 16, v16
	v_pk_fma_f32 v[20:21], v[92:93], v[34:35], v[20:21] op_sel:[0,0,1] op_sel_hi:[1,0,0]
	v_and_b32_e32 v41, 0xffff0000, v16
	v_pk_fma_f32 v[20:21], v[90:91], v[36:37], v[20:21] op_sel_hi:[0,1,1]
	v_lshlrev_b32_e32 v16, 16, v17
	v_and_b32_e32 v17, 0xffff0000, v17
	v_pk_add_f32 v[20:21], v[94:95], v[20:21] op_sel_hi:[0,1]
	v_pk_mul_f32 v[38:39], v[102:103], v[40:41] op_sel_hi:[0,1]
	v_cvt_pk_bf16_f32 v20, v20, v21
	v_pk_mul_f32 v[16:17], v[102:103], v[16:17] op_sel_hi:[0,1]
	v_pk_fma_f32 v[24:25], v[104:105], v[24:25], v[38:39] op_sel_hi:[0,1,1]
	v_and_b32_e32 v21, 0xffff0000, v20
	v_lshlrev_b32_e32 v20, 16, v20
	v_pk_fma_f32 v[16:17], v[104:105], v[26:27], v[16:17] op_sel_hi:[0,1,1]
	v_pk_mul_f32 v[20:21], v[24:25], v[20:21]
	v_pk_mul_f32 v[16:17], v[16:17], v[22:23]
	v_cvt_pk_bf16_f32 v20, v20, v21
	v_cvt_pk_bf16_f32 v21, v16, v17
	global_load_dwordx2 v[16:17], v[32:33], off offset:48
	global_load_ushort v24, v54, s[0:1] offset:-2
	v_lshl_add_u64 v[22:23], s[0:1], 0, v[48:49]
	global_load_ushort v22, v[22:23], off offset:8
	s_or_b32 s0, vcc_lo, 0xb00
	s_add_u32 s0, s0, s12
	v_lshlrev_b32_e32 v34, 16, v18
	v_and_b32_e32 v35, 0xffff0000, v18
	v_lshlrev_b32_e32 v18, 16, v19
	v_and_b32_e32 v19, 0xffff0000, v19
	s_addc_u32 s1, 0, s13
	v_pk_mul_f32 v[18:19], v[102:103], v[18:19] op_sel_hi:[0,1]
	s_lshl_b64 s[0:1], s[0:1], 13
	v_pk_fma_f32 v[18:19], v[104:105], v[30:31], v[18:19] op_sel_hi:[0,1,1]
	s_add_u32 s0, s8, s0
	s_addc_u32 s1, s9, s1
	v_mov_b32_e32 v43, v63
	v_mov_b32_e32 v42, v63
	v_mov_b32_e32 v41, v63
	v_mov_b32_e32 v40, v63
	v_mov_b32_e32 v39, v63
	v_mov_b32_e32 v38, v63
	s_waitcnt vmcnt(2)
	v_lshlrev_b32_e32 v33, 16, v17
	s_waitcnt vmcnt(1)
	v_lshlrev_b32_e32 v24, 16, v24
	v_lshlrev_b32_e32 v26, 16, v16
	v_and_b32_e32 v32, 0xffff0000, v16
	v_and_b32_e32 v17, 0xffff0000, v17
	v_mov_b32_e32 v16, v33
	v_cndmask_b32_e64 v25, 0, v24, s[36:37]
	s_waitcnt vmcnt(0)
	v_lshlrev_b32_e32 v22, 16, v22
	v_pk_mul_f32 v[36:37], v[92:93], v[16:17] op_sel_hi:[0,1]
	v_mov_b32_e32 v24, v32
	v_cndmask_b32_e64 v23, 0, v22, s[38:39]
	v_pk_fma_f32 v[36:37], v[96:97], v[32:33], v[36:37] op_sel_hi:[0,1,1]
	v_mov_b32_e32 v22, v17
	v_pk_mul_f32 v[24:25], v[92:93], v[24:25]
	v_pk_fma_f32 v[16:17], v[90:91], v[22:23], v[36:37] op_sel_hi:[0,1,1]
	v_pk_fma_f32 v[24:25], v[92:93], v[26:27], v[24:25] op_sel:[0,0,1] op_sel_hi:[1,0,0]
	v_pk_add_f32 v[16:17], v[94:95], v[16:17] op_sel_hi:[0,1]
	v_pk_fma_f32 v[24:25], v[90:91], v[32:33], v[24:25] op_sel_hi:[0,1,1]
	v_cvt_pk_bf16_f32 v16, v16, v17
	v_pk_add_f32 v[24:25], v[94:95], v[24:25] op_sel_hi:[0,1]
	v_and_b32_e32 v17, 0xffff0000, v16
	v_lshlrev_b32_e32 v16, 16, v16
	v_pk_mul_f32 v[22:23], v[102:103], v[34:35] op_sel_hi:[0,1]
	v_cvt_pk_bf16_f32 v24, v24, v25
	v_pk_fma_f32 v[22:23], v[104:105], v[28:29], v[22:23] op_sel_hi:[0,1,1]
	v_and_b32_e32 v25, 0xffff0000, v24
	v_lshlrev_b32_e32 v24, 16, v24
	v_pk_mul_f32 v[16:17], v[18:19], v[16:17]
	v_pk_mul_f32 v[22:23], v[22:23], v[24:25]
	v_cvt_pk_bf16_f32 v19, v16, v17
	v_lshl_add_u64 v[16:17], s[0:1], 0, v[76:77]
	v_cvt_pk_bf16_f32 v18, v22, v23
	global_load_dwordx2 v[16:17], v[16:17], off
	ds_write2_b64 v114, v[20:21], v[18:19] offset0:68 offset1:70
	v_lshl_add_u64 v[18:19], s[0:1], 0, v[78:79]
	global_load_ushort v18, v[18:19], off offset:8
	v_mov_b32_e32 v37, v63
	global_load_ushort v20, v81, s[0:1] offset:-2
	v_mov_b32_e32 v36, v63
	v_mov_b32_e32 v35, v63
	v_mov_b32_e32 v34, v63
	s_waitcnt vmcnt(2)
	v_lshlrev_b32_e32 v27, 16, v17
	v_and_b32_e32 v29, 0xffff0000, v17
	v_mov_b32_e32 v28, v27
	s_waitcnt vmcnt(1)
	v_lshlrev_b32_e32 v18, 16, v18
	v_and_b32_e32 v26, 0xffff0000, v16
	v_pk_mul_f32 v[32:33], v[92:93], v[28:29] op_sel_hi:[0,1]
	v_cndmask_b32_e64 v23, 0, v18, s[48:49]
	v_pk_fma_f32 v[32:33], v[96:97], v[26:27], v[32:33] op_sel_hi:[0,1,1]
	v_mov_b32_e32 v22, v29
	v_pk_fma_f32 v[22:23], v[90:91], v[22:23], v[32:33] op_sel_hi:[0,1,1]
	s_waitcnt vmcnt(0)
	v_lshlrev_b32_e32 v20, 16, v20
	v_pk_add_f32 v[22:23], v[94:95], v[22:23] op_sel_hi:[0,1]
	v_cndmask_b32_e64 v21, 0, v20, s[50:51]
	v_lshlrev_b32_e32 v24, 16, v16
	ds_read2_b64 v[16:19], v115 offset0:192 offset1:194
	v_cvt_pk_bf16_f32 v20, v22, v23
	v_and_b32_e32 v23, 0xffff0000, v20
	v_lshlrev_b32_e32 v22, 16, v20
	v_mov_b32_e32 v20, v26
	v_pk_mul_f32 v[20:21], v[92:93], v[20:21]
	s_waitcnt lgkmcnt(0)
; DI unsigned pack2(float lo, float hi) { f32x2_t v = {lo, hi}; bf16x2_t r = __builtin_convertvector(v, bf16x2_t); return __builtin_bit_cast(unsigned, r); }
; DI bf16_t f2bf(float x) { return (bf16_t)(pack2(x, x) & 0xffffu); }
; DI float bf2f(bf16_t v) { return __uint_as_float(((unsigned)v) << 16); }
; DI float rbf(float x) { return bf2f(f2bf(x)); }
; DI void hy_conv4(const HyRaw4& r, int t0, float w0, float w1, float w2, float wb, float (&o)[4]) {
;   const float xm = t0 > 0 ? bf2f(r.m) : 0.f, xp = t0 + 4 < SEQ ? bf2f(r.pz) : 0.f;
;   const float e0 = bf2f((bf16_t)(r.v.x & 0xffff)), e1 = bf2f((bf16_t)(r.v.x >> 16)), e2 = bf2f((bf16_t)(r.v.y & 0xffff)), e3 = bf2f((bf16_t)(r.v.y >> 16));
;   o[0] = rbf(xm * w0 + e0 * w1 + e1 * w2 + wb);
;   o[1] = rbf(e0 * w0 + e1 * w1 + e2 * w2 + wb);
;   o[2] = rbf(e1 * w0 + e2 * w1 + e3 * w2 + wb);
;   o[3] = rbf(e2 * w0 + e3 * w1 + xp * w2 + wb);
; }
; DI void hyena_item(const Params& p, int layer, int c, int bh, char* smem) {
;     ...
;   for (int bb = 0; bb < 4; ++bb) {
;     const bf16_t* x1 = HT + (((size_t)1 * NB + bh * 4 + bb) * 256 + c) * SEQ;
;     bf16_t* zw = sZ + bb * ZROW;
; #pragma unroll
;     for (int g = 0; g < 4; ++g) {
;       const int off = 8 * g + 4 * h;
;       float xa[4];
;       hy_conv4(hy_raw4(x1, i * 32 + off), i * 32 + off, aw0, aw1, aw2, awb, xa);
;       uint2* zp = (uint2*)(zw + (i + 32) * ZB + off);
;       uint2 vv = *zp;
;       float z0 = xa[0] * (acc[bb][4 * g + 0] * inv0 + bf2f((bf16_t)(vv.x & 0xffff)) * bias0);
;       float z1 = xa[1] * (acc[bb][4 * g + 1] * inv0 + bf2f((bf16_t)(vv.x >> 16)) * bias0);
;       float z2 = xa[2] * (acc[bb][4 * g + 2] * inv0 + bf2f((bf16_t)(vv.y & 0xffff)) * bias0);
;       float z3 = xa[3] * (acc[bb][4 * g + 3] * inv0 + bf2f((bf16_t)(vv.y >> 16)) * bias0);
;       uint2 o; o.x = pack2(z0, z1); o.y = pack2(z2, z3);
;       *zp = o;
;     }
;   }
;   __syncthreads();
	v_lshlrev_b32_e32 v30, 16, v16
	v_pk_fma_f32 v[20:21], v[92:93], v[24:25], v[20:21] op_sel:[0,0,1] op_sel_hi:[1,0,0]
	v_and_b32_e32 v31, 0xffff0000, v16
	v_pk_fma_f32 v[20:21], v[90:91], v[26:27], v[20:21] op_sel_hi:[0,1,1]
	v_lshlrev_b32_e32 v16, 16, v17
	v_and_b32_e32 v17, 0xffff0000, v17
	v_pk_add_f32 v[20:21], v[94:95], v[20:21] op_sel_hi:[0,1]
	v_pk_mul_f32 v[28:29], v[102:103], v[30:31] op_sel_hi:[0,1]
	v_cvt_pk_bf16_f32 v20, v20, v21
	v_pk_mul_f32 v[16:17], v[102:103], v[16:17] op_sel_hi:[0,1]
	v_pk_fma_f32 v[0:1], v[104:105], v[0:1], v[28:29] op_sel_hi:[0,1,1]
	v_and_b32_e32 v21, 0xffff0000, v20
	v_lshlrev_b32_e32 v20, 16, v20
	v_pk_fma_f32 v[2:3], v[104:105], v[2:3], v[16:17] op_sel_hi:[0,1,1]
	v_pk_mul_f32 v[0:1], v[0:1], v[20:21]
	v_pk_mul_f32 v[2:3], v[2:3], v[22:23]
	v_lshl_add_u64 v[16:17], s[0:1], 0, v[50:51]
	v_cvt_pk_bf16_f32 v0, v0, v1
	v_cvt_pk_bf16_f32 v1, v2, v3
	global_load_dwordx2 v[2:3], v[16:17], off offset:16
	v_lshl_add_u64 v[20:21], s[0:1], 0, v[72:73]
	global_load_ushort v20, v[20:21], off offset:8
	v_lshlrev_b32_e32 v28, 16, v18
	global_load_ushort v22, v101, s[0:1] offset:-2
	v_and_b32_e32 v29, 0xffff0000, v18
	v_lshlrev_b32_e32 v18, 16, v19
	v_and_b32_e32 v19, 0xffff0000, v19
	v_pk_mul_f32 v[18:19], v[102:103], v[18:19] op_sel_hi:[0,1]
	v_pk_fma_f32 v[6:7], v[104:105], v[6:7], v[18:19] op_sel_hi:[0,1,1]
	v_mov_b32_e32 v51, v63
	v_mov_b32_e32 v50, v63
	v_mov_b32_e32 v33, v63
	v_mov_b32_e32 v32, v63
	s_waitcnt vmcnt(2)
	v_lshlrev_b32_e32 v27, 16, v3
	v_lshlrev_b32_e32 v24, 16, v2
	v_and_b32_e32 v26, 0xffff0000, v2
	v_and_b32_e32 v3, 0xffff0000, v3
	v_mov_b32_e32 v2, v27
	s_waitcnt vmcnt(1)
	v_lshlrev_b32_e32 v20, 16, v20
	v_pk_mul_f32 v[30:31], v[92:93], v[2:3] op_sel_hi:[0,1]
	s_waitcnt vmcnt(0)
	v_lshlrev_b32_e32 v22, 16, v22
	v_cndmask_b32_e64 v21, 0, v20, s[46:47]
	v_pk_fma_f32 v[30:31], v[96:97], v[26:27], v[30:31] op_sel_hi:[0,1,1]
	v_mov_b32_e32 v20, v3
	v_cndmask_b32_e64 v23, 0, v22, s[44:45]
	v_pk_fma_f32 v[2:3], v[90:91], v[20:21], v[30:31] op_sel_hi:[0,1,1]
	v_pk_mul_f32 v[20:21], v[102:103], v[28:29] op_sel_hi:[0,1]
	v_mov_b32_e32 v22, v26
	v_pk_fma_f32 v[4:5], v[104:105], v[4:5], v[20:21] op_sel_hi:[0,1,1]
	v_pk_mul_f32 v[20:21], v[92:93], v[22:23]
	v_pk_add_f32 v[2:3], v[94:95], v[2:3] op_sel_hi:[0,1]
	v_pk_fma_f32 v[20:21], v[92:93], v[24:25], v[20:21] op_sel:[0,0,1] op_sel_hi:[1,0,0]
	v_cvt_pk_bf16_f32 v2, v2, v3
	v_pk_fma_f32 v[20:21], v[90:91], v[26:27], v[20:21] op_sel_hi:[0,1,1]
	v_pk_add_f32 v[20:21], v[94:95], v[20:21] op_sel_hi:[0,1]
	v_cvt_pk_bf16_f32 v20, v20, v21
	v_and_b32_e32 v3, 0xffff0000, v2
	v_lshlrev_b32_e32 v2, 16, v2
	v_and_b32_e32 v21, 0xffff0000, v20
	v_lshlrev_b32_e32 v20, 16, v20
	v_pk_mul_f32 v[4:5], v[4:5], v[20:21]
	v_pk_mul_f32 v[2:3], v[6:7], v[2:3]
	v_cvt_pk_bf16_f32 v4, v4, v5
	v_cvt_pk_bf16_f32 v5, v2, v3
	ds_write2_b64 v115, v[0:1], v[4:5] offset0:192 offset1:194
	global_load_dwordx2 v[0:1], v[16:17], off offset:32
	global_load_ushort v4, v55, s[0:1] offset:-2
	v_lshl_add_u64 v[2:3], s[0:1], 0, v[52:53]
	global_load_ushort v2, v[2:3], off offset:8
	v_mov_b32_e32 v55, v63
	v_mov_b32_e32 v53, v63
	v_mov_b32_e32 v52, v63
	v_mov_b32_e32 v31, v63
	v_mov_b32_e32 v30, v63
	v_mov_b32_e32 v29, v63
	v_mov_b32_e32 v28, v63
	s_waitcnt vmcnt(2)
	v_lshlrev_b32_e32 v21, 16, v1
	v_and_b32_e32 v23, 0xffff0000, v1
	v_mov_b32_e32 v22, v21
	s_waitcnt vmcnt(0)
	v_lshlrev_b32_e32 v2, 16, v2
	v_and_b32_e32 v20, 0xffff0000, v0
	v_pk_mul_f32 v[26:27], v[92:93], v[22:23] op_sel_hi:[0,1]
	v_cndmask_b32_e64 v7, 0, v2, s[42:43]
	v_pk_fma_f32 v[26:27], v[96:97], v[20:21], v[26:27] op_sel_hi:[0,1,1]
	v_mov_b32_e32 v6, v23
	v_pk_fma_f32 v[6:7], v[90:91], v[6:7], v[26:27] op_sel_hi:[0,1,1]
	v_lshlrev_b32_e32 v4, 16, v4
	v_pk_add_f32 v[6:7], v[94:95], v[6:7] op_sel_hi:[0,1]
	v_cndmask_b32_e64 v5, 0, v4, s[40:41]
	v_lshlrev_b32_e32 v18, 16, v0
	ds_read2_b64 v[0:3], v115 offset0:196 offset1:198
	v_cvt_pk_bf16_f32 v4, v6, v7
	v_and_b32_e32 v7, 0xffff0000, v4
	v_lshlrev_b32_e32 v6, 16, v4
	v_mov_b32_e32 v4, v20
	v_pk_mul_f32 v[4:5], v[92:93], v[4:5]
	s_waitcnt lgkmcnt(0)
	v_lshlrev_b32_e32 v24, 16, v0
	v_pk_fma_f32 v[4:5], v[92:93], v[18:19], v[4:5] op_sel:[0,0,1] op_sel_hi:[1,0,0]
	v_and_b32_e32 v25, 0xffff0000, v0
	v_pk_fma_f32 v[4:5], v[90:91], v[20:21], v[4:5] op_sel_hi:[0,1,1]
	v_pk_add_f32 v[4:5], v[94:95], v[4:5] op_sel_hi:[0,1]
	v_lshlrev_b32_e32 v0, 16, v1
	v_and_b32_e32 v1, 0xffff0000, v1
	v_pk_mul_f32 v[22:23], v[102:103], v[24:25] op_sel_hi:[0,1]
	v_cvt_pk_bf16_f32 v4, v4, v5
	v_pk_fma_f32 v[8:9], v[104:105], v[8:9], v[22:23] op_sel_hi:[0,1,1]
	v_and_b32_e32 v5, 0xffff0000, v4
	v_lshlrev_b32_e32 v4, 16, v4
	v_pk_mul_f32 v[0:1], v[102:103], v[0:1] op_sel_hi:[0,1]
	v_pk_mul_f32 v[4:5], v[8:9], v[4:5]
	v_pk_fma_f32 v[0:1], v[104:105], v[10:11], v[0:1] op_sel_hi:[0,1,1]
	v_pk_mul_f32 v[6:7], v[0:1], v[6:7]
	v_cvt_pk_bf16_f32 v0, v4, v5
	global_load_dwordx2 v[4:5], v[16:17], off offset:48
	global_load_ushort v8, v54, s[0:1] offset:-2
	v_cvt_pk_bf16_f32 v1, v6, v7
	v_lshl_add_u64 v[6:7], s[0:1], 0, v[48:49]
	global_load_ushort v6, v[6:7], off offset:8
	v_lshlrev_b32_e32 v18, 16, v2
	v_and_b32_e32 v19, 0xffff0000, v2
	v_lshlrev_b32_e32 v2, 16, v3
	v_and_b32_e32 v3, 0xffff0000, v3
	v_pk_mul_f32 v[2:3], v[102:103], v[2:3] op_sel_hi:[0,1]
	v_pk_fma_f32 v[2:3], v[104:105], v[14:15], v[2:3] op_sel_hi:[0,1,1]
	v_mov_b32_e32 v54, v63
	v_mov_b32_e32 v49, v63
	v_mov_b32_e32 v48, v63
	v_mov_b32_e32 v27, v63
	v_mov_b32_e32 v26, v63
	v_mov_b32_e32 v25, v63
	v_mov_b32_e32 v24, v63
	v_mov_b32_e32 v23, v63
	v_mov_b32_e32 v22, v63
	v_mov_b32_e32 v15, v63
	v_mov_b32_e32 v14, v63
	s_waitcnt vmcnt(2)
	v_and_b32_e32 v16, 0xffff0000, v4
	s_waitcnt vmcnt(1)
	v_lshlrev_b32_e32 v8, 16, v8
	v_lshlrev_b32_e32 v17, 16, v5
	v_cndmask_b32_e64 v9, 0, v8, s[36:37]
	v_lshlrev_b32_e32 v10, 16, v4
	v_and_b32_e32 v5, 0xffff0000, v5
	v_mov_b32_e32 v4, v17
	v_mov_b32_e32 v8, v16
	s_waitcnt vmcnt(0)
	v_lshlrev_b32_e32 v6, 16, v6
	v_pk_mul_f32 v[20:21], v[92:93], v[4:5] op_sel_hi:[0,1]
	v_pk_mul_f32 v[8:9], v[92:93], v[8:9]
	v_cndmask_b32_e64 v7, 0, v6, s[38:39]
	v_pk_fma_f32 v[20:21], v[96:97], v[16:17], v[20:21] op_sel_hi:[0,1,1]
	v_mov_b32_e32 v6, v5
	v_pk_fma_f32 v[8:9], v[92:93], v[10:11], v[8:9] op_sel:[0,0,1] op_sel_hi:[1,0,0]
	v_pk_fma_f32 v[4:5], v[90:91], v[6:7], v[20:21] op_sel_hi:[0,1,1]
	v_pk_fma_f32 v[8:9], v[90:91], v[16:17], v[8:9] op_sel_hi:[0,1,1]
	v_pk_add_f32 v[4:5], v[94:95], v[4:5] op_sel_hi:[0,1]
	v_pk_add_f32 v[8:9], v[94:95], v[8:9] op_sel_hi:[0,1]
	v_cvt_pk_bf16_f32 v4, v4, v5
	v_pk_mul_f32 v[6:7], v[102:103], v[18:19] op_sel_hi:[0,1]
	v_cvt_pk_bf16_f32 v8, v8, v9
	v_and_b32_e32 v5, 0xffff0000, v4
	v_lshlrev_b32_e32 v4, 16, v4
	v_pk_fma_f32 v[6:7], v[104:105], v[12:13], v[6:7] op_sel_hi:[0,1,1]
	v_and_b32_e32 v9, 0xffff0000, v8
	v_lshlrev_b32_e32 v8, 16, v8
	v_pk_mul_f32 v[6:7], v[6:7], v[8:9]
	v_pk_mul_f32 v[2:3], v[2:3], v[4:5]
	v_cvt_pk_bf16_f32 v4, v6, v7
	v_cvt_pk_bf16_f32 v5, v2, v3
	ds_write2_b64 v115, v[0:1], v[4:5] offset0:196 offset1:198
	s_waitcnt lgkmcnt(0)
	s_barrier
; DI bf16x8 toeplitz_frag(const u32x4& lo, const u32x4& hi, bool b0, bool b1, unsigned sh) {
;   const unsigned d0 = lo[0], d1 = lo[1], d2 = lo[2], d3 = lo[3], d4 = hi[0], d5 = hi[1], d6 = hi[2], d7 = hi[3];
;   const unsigned t0 = b0 ? d1 : d0, t1 = b0 ? d2 : d1, t2 = b0 ? d3 : d2, t3 = b0 ? d4 : d3, t4 = b0 ? d5 : d4, t5 = b0 ? d6 : d5, t6 = b0 ? d7 : d6;
;   const unsigned e0 = b1 ? t2 : t0, e1 = b1 ? t3 : t1, e2 = b1 ? t4 : t2, e3 = b1 ? t5 : t3, e4 = b1 ? t6 : t4;
;   u32x4 o = {__builtin_amdgcn_alignbit(e1, e0, sh), __builtin_amdgcn_alignbit(e2, e1, sh), __builtin_amdgcn_alignbit(e3, e2, sh),
;              __builtin_amdgcn_alignbit(e4, e3, sh)};
;   return __builtin_bit_cast(bf16x8, o);
; }
; DI void hyena_conv(const bf16_t* sK, const bf16_t* sZ, f32x16 (&acc)[4], int q, int lane) {
;   const int r = lane & 31, h = lane >> 5;
;   const int phi = (7 - r) & 7;
;   const bool pb0 = (phi >> 1) & 1, pb1 = (phi >> 2) & 1;
;   const unsigned psh = (phi & 1) * 16;
; #pragma unroll
;   for (int bb = 0; bb < 4; ++bb)
; #pragma unroll
;     for (int i = 0; i < 16; ++i) acc[bb][i] = 0.f;
;   int dlo = 32 * q - 127, dhi = 32 * q + 31;
;   asm volatile("" : "+s"(dlo), "+s"(dhi));
;   for (int d = dlo; d < dhi; d += 2) {
;     HY_BODY(d)
;     HY_BODY(d + 1)
;   }
;   HY_BODY(dhi)
; }
	s_cmp_lt_i32 s28, s11
	v_mov_b32_e32 v21, v63
	v_mov_b32_e32 v20, v63
	v_mov_b32_e32 v19, v63
	v_mov_b32_e32 v18, v63
	v_mov_b32_e32 v17, v63
	v_mov_b32_e32 v16, v63
	v_mov_b32_e32 v13, v63
	v_mov_b32_e32 v12, v63
	v_mov_b32_e32 v11, v63
	v_mov_b32_e32 v10, v63
	v_mov_b32_e32 v9, v63
	v_mov_b32_e32 v8, v63
	v_mov_b32_e32 v7, v63
	v_mov_b32_e32 v6, v63
	v_mov_b32_e32 v5, v63
	v_mov_b32_e32 v4, v63
	v_mov_b32_e32 v3, v63
	v_mov_b32_e32 v2, v63
	v_mov_b32_e32 v1, v63
	v_mov_b32_e32 v0, v63
	s_cbranch_scc0 .LBB0_567
	v_subrev_u32_e32 v0, s28, v105
	s_movk_i32 s1, 0x50
	v_mul_lo_u32 v0, v0, s1
	s_lshl_b32 s0, s28, 6
	v_add_u32_e32 v90, 0xa00, v0
	v_lshl_add_u32 v0, v103, 1, s0
	v_sub_u32_e32 v92, 0, v0
	v_mov_b32_e32 v0, s29
	v_mad_u32_u24 v0, v97, s1, v0
	s_mul_i32 s0, s28, 0x50
	v_subrev_u32_e32 v0, s0, v0
	v_add_u32_e32 v93, 0x9b0, v0
	v_mov_b32_e32 v0, 0
	s_movk_i32 s27, 0x50
	v_mov_b32_e32 v1, v0
	v_mov_b32_e32 v2, v0
	v_mov_b32_e32 v3, v0
	v_mov_b32_e32 v4, v0
	v_mov_b32_e32 v5, v0
	v_mov_b32_e32 v6, v0
	v_mov_b32_e32 v7, v0
	v_mov_b32_e32 v8, v0
	v_mov_b32_e32 v9, v0
	v_mov_b32_e32 v10, v0
	v_mov_b32_e32 v11, v0
	v_mov_b32_e32 v12, v0
	v_mov_b32_e32 v13, v0
	v_mov_b32_e32 v14, v0
	v_mov_b32_e32 v15, v0
	v_mov_b32_e32 v16, v0
	v_mov_b32_e32 v17, v0
	v_mov_b32_e32 v18, v0
	v_mov_b32_e32 v19, v0
	v_mov_b32_e32 v20, v0
	v_mov_b32_e32 v21, v0
	v_mov_b32_e32 v22, v0
	v_mov_b32_e32 v23, v0
	v_mov_b32_e32 v24, v0
	v_mov_b32_e32 v25, v0
	v_mov_b32_e32 v26, v0
	v_mov_b32_e32 v27, v0
	v_mov_b32_e32 v28, v0
	v_mov_b32_e32 v29, v0
	v_mov_b32_e32 v30, v0
	v_mov_b32_e32 v31, v0
	v_mov_b32_e32 v32, v0
	v_mov_b32_e32 v33, v0
	v_mov_b32_e32 v34, v0
	v_mov_b32_e32 v35, v0
	v_mov_b32_e32 v36, v0
	v_mov_b32_e32 v37, v0
	v_mov_b32_e32 v38, v0
	v_mov_b32_e32 v39, v0
	v_mov_b32_e32 v40, v0
	v_mov_b32_e32 v41, v0
	v_mov_b32_e32 v42, v0
	v_mov_b32_e32 v43, v0
	v_mov_b32_e32 v44, v0
	v_mov_b32_e32 v45, v0
	v_mov_b32_e32 v46, v0
	v_mov_b32_e32 v47, v0
	v_mov_b32_e32 v48, v0
	v_mov_b32_e32 v49, v0
	v_mov_b32_e32 v50, v0
	v_mov_b32_e32 v51, v0
	v_mov_b32_e32 v52, v0
	v_mov_b32_e32 v53, v0
	v_mov_b32_e32 v54, v0
	v_mov_b32_e32 v55, v0
	v_mov_b32_e32 v56, v0
	v_mov_b32_e32 v57, v0
	v_mov_b32_e32 v58, v0
	v_mov_b32_e32 v59, v0
	v_mov_b32_e32 v60, v0
	v_mov_b32_e32 v61, v0
	v_mov_b32_e32 v62, v0
	v_mov_b32_e32 v63, v0
	v_and_b32_e32 v241, 6, v85
	v_lshl_add_u32 v241, v241, 1, v87
	v_add_u32_e32 v241, 0x10fbe, v241
	v_add_u32_e32 v240, v92, v241
	ds_read2_b32 v[242:243], v240 offset0:16 offset1:17
	ds_read2_b32 v[244:245], v240 offset0:18 offset1:19
	ds_read2_b32 v[246:247], v240 offset0:20 offset1:24
	ds_read2_b32 v[248:249], v240 offset0:25 offset1:26
	ds_read2_b32 v[250:251], v240 offset0:27 offset1:28
	v_add_u32_e32 v96, v90, v87
	ds_read_b128 v[144:147], v96
	ds_read_b128 v[148:151], v96 offset:32
	ds_read_b128 v[152:155], v96 offset:15360
	ds_read_b128 v[156:159], v96 offset:15392
	ds_read_b128 v[160:163], v96 offset:30720
	ds_read_b128 v[164:167], v96 offset:30752
	ds_read_b128 v[168:171], v96 offset:46080
	ds_read_b128 v[172:175], v96 offset:46112
.LBB0_585:
	s_waitcnt lgkmcnt(0)
	v_alignbit_b32 v68, v243, v242, v83
	v_alignbit_b32 v69, v244, v243, v83
	v_alignbit_b32 v70, v245, v244, v83
	v_alignbit_b32 v71, v246, v245, v83
	v_alignbit_b32 v72, v248, v247, v83
	v_alignbit_b32 v73, v249, v248, v83
	v_alignbit_b32 v74, v250, v249, v83
	v_alignbit_b32 v75, v251, v250, v83
	ds_read2_b32 v[242:243], v240 offset0:0 offset1:1
	ds_read2_b32 v[244:245], v240 offset0:2 offset1:3
	ds_read2_b32 v[246:247], v240 offset0:4 offset1:8
	ds_read2_b32 v[248:249], v240 offset0:9 offset1:10
	ds_read2_b32 v[250:251], v240 offset0:11 offset1:12
	v_add_u32_e32 v94, v93, v87
	v_mfma_f32_32x32x16_bf16 v[48:63], v[68:71], v[144:147], v[48:63]
	ds_read_b128 v[176:179], v94
	v_mfma_f32_32x32x16_bf16 v[48:63], v[72:75], v[148:151], v[48:63]
	ds_read_b128 v[180:183], v94 offset:32
	s_add_i32 s28, s28, 2
	v_add_u32_e32 v90, 0xffffff60, v90
	v_add_u32_e32 v92, 0xffffff80, v92
	s_cmp_lt_i32 s28, s11
	v_mfma_f32_32x32x16_bf16 v[32:47], v[68:71], v[152:155], v[32:47]
	ds_read_b128 v[184:187], v94 offset:15360
	v_mfma_f32_32x32x16_bf16 v[32:47], v[72:75], v[156:159], v[32:47]
	ds_read_b128 v[212:215], v94 offset:15392
	v_mfma_f32_32x32x16_bf16 v[16:31], v[68:71], v[160:163], v[16:31]
	ds_read_b128 v[216:219], v94 offset:30720
	v_mfma_f32_32x32x16_bf16 v[16:31], v[72:75], v[164:167], v[16:31]
	ds_read_b128 v[220:223], v94 offset:30752
	v_mfma_f32_32x32x16_bf16 v[0:15], v[68:71], v[168:171], v[0:15]
	ds_read_b128 v[224:227], v94 offset:46080
	v_mfma_f32_32x32x16_bf16 v[0:15], v[72:75], v[172:175], v[0:15]
	ds_read_b128 v[228:231], v94 offset:46112
	s_waitcnt lgkmcnt(0)
	v_alignbit_b32 v68, v243, v242, v83
	v_alignbit_b32 v69, v244, v243, v83
	v_alignbit_b32 v70, v245, v244, v83
	v_alignbit_b32 v71, v246, v245, v83
	v_alignbit_b32 v72, v248, v247, v83
	v_alignbit_b32 v73, v249, v248, v83
	v_alignbit_b32 v74, v250, v249, v83
	v_alignbit_b32 v75, v251, v250, v83
	v_add_u32_e32 v240, v92, v241
	ds_read2_b32 v[242:243], v240 offset0:16 offset1:17
	ds_read2_b32 v[244:245], v240 offset0:18 offset1:19
	ds_read2_b32 v[246:247], v240 offset0:20 offset1:24
	ds_read2_b32 v[248:249], v240 offset0:25 offset1:26
	ds_read2_b32 v[250:251], v240 offset0:27 offset1:28
	v_add_u32_e32 v96, v90, v87
	v_mfma_f32_32x32x16_bf16 v[48:63], v[68:71], v[176:179], v[48:63]
	ds_read_b128 v[144:147], v96
	v_mfma_f32_32x32x16_bf16 v[48:63], v[72:75], v[180:183], v[48:63]
	ds_read_b128 v[148:151], v96 offset:32
	v_add_u32_e32 v93, 0xffffff60, v93
	v_mfma_f32_32x32x16_bf16 v[32:47], v[68:71], v[184:187], v[32:47]
	ds_read_b128 v[152:155], v96 offset:15360
	v_mfma_f32_32x32x16_bf16 v[32:47], v[72:75], v[212:215], v[32:47]
	ds_read_b128 v[156:159], v96 offset:15392
	v_mfma_f32_32x32x16_bf16 v[16:31], v[68:71], v[216:219], v[16:31]
	ds_read_b128 v[160:163], v96 offset:30720
	v_mfma_f32_32x32x16_bf16 v[16:31], v[72:75], v[220:223], v[16:31]
	ds_read_b128 v[164:167], v96 offset:30752
	v_mfma_f32_32x32x16_bf16 v[0:15], v[68:71], v[224:227], v[0:15]
	ds_read_b128 v[168:171], v96 offset:46080
	v_mfma_f32_32x32x16_bf16 v[0:15], v[72:75], v[228:231], v[0:15]
	ds_read_b128 v[172:175], v96 offset:46112
	s_cbranch_scc1 .LBB0_585
	s_branch .LBB0_567
